# FFN-up epilogue: g*v product placed between the exp pair and its consumer (s_nop dropped); no-max loop: first two PV MFMAs share one lgkmcnt wait
# speedup vs baseline: 1.0090x; 1.0011x over previous
; #define GAS __attribute__((address_space(1)))
;     __device__ __forceinline__ void conv4(const f32x4& a0, const f32x4& a1, const f32x4& a2, const f32x4& a3, const f32x4& w0, const f32x4& w1, const f32x4& w2, const f32x4& b, f32x2 (&h)[4][2]) const {
; #pragma unroll
;         for (int p = 0; p < 2; ++p) {
;             float u0, u1, d0, d1;
;             asm volatile("s_nop 1\n\tv_mov_b32_dpp %0, %1 row_shr:1 row_mask:0xf bank_mask:0xf bound_ctrl:1" : "=&v"(u0) : "v"(a3[2 * p]));
;             asm volatile("s_nop 1\n\tv_mov_b32_dpp %0, %1 row_shr:1 row_mask:0xf bank_mask:0xf bound_ctrl:1" : "=&v"(u1) : "v"(a3[2 * p + 1]));
;             asm volatile("s_nop 1\n\tv_mov_b32_dpp %0, %1 row_shl:1 row_mask:0xf bank_mask:0xf bound_ctrl:1" : "=&v"(d0) : "v"(a0[2 * p]));
;             asm volatile("s_nop 1\n\tv_mov_b32_dpp %0, %1 row_shl:1 row_mask:0xf bank_mask:0xf bound_ctrl:1" : "=&v"(d1) : "v"(a0[2 * p + 1]));
;             const f32x2 UP = {u0, u1}, DN = {d0, d1};
;             const f32x2 A0 = {a0[2 * p], a0[2 * p + 1]}, A1 = {a1[2 * p], a1[2 * p + 1]}, A2 = {a2[2 * p], a2[2 * p + 1]}, A3 = {a3[2 * p], a3[2 * p + 1]};
;             const f32x2 W0 = {w0[2 * p], w0[2 * p + 1]}, W1 = {w1[2 * p], w1[2 * p + 1]}, W2 = {w2[2 * p], w2[2 * p + 1]}, B = {b[2 * p], b[2 * p + 1]};
;             h[0][p] = B + W0 * UP + W1 * A0 + W2 * A1;
;             h[1][p] = B + W0 * A0 + W1 * A1 + W2 * A2;
;             h[2][p] = B + W0 * A1 + W1 * A2 + W2 * A3;
;             h[3][p] = B + W0 * A2 + W1 * A3 + W2 * DN;
;         }
;     }
;     static __device__ __forceinline__ unsigned silu_pk(const f32x2 g, const f32x2 v) {
;         const f32x2 t = g * -1.4426950408889634f;
;         const f32x2 d = (f32x2){__builtin_amdgcn_exp2f(t.x), __builtin_amdgcn_exp2f(t.y)} + 1.0f;
;         const f32x2 o = g * v * (f32x2){__builtin_amdgcn_rcpf(d.x), __builtin_amdgcn_rcpf(d.y)};
;         return cvt_pk_bf16(o.x, o.y);
;     }
;     __device__ __forceinline__ void operator()(f32x4 (&acc)[2][2][4][2], const Unit& u, int wr, int wc, int lane) const {
;         const int fr = lane & 15, fq = lane >> 4;
;         const int colu = u.pn * 128 + wc * 32;
;         const GAS float* cwu = cw + colu; const GAS float* cbu = cb + colu;
;         u32x2 keep[2][4];
;         f32x4 wgt[2][8];
; #pragma unroll
;         for (int n = 0; n < 2; ++n) { const unsigned co = (unsigned)(8 * fq + 4 * n) * 4u;
.LBB0_134:
	s_lshl_b32 s17, s52, 7
	s_or_b32 s48, s17, s37
	s_ashr_i32 s49, s48, 31
	s_lshl_b64 s[42:43], s[48:49], 2
	v_mbcnt_lo_u32_b32 v230, -1, 0
	v_mbcnt_hi_u32_b32 v230, -1, v230
	s_add_u32 s44, s0, s42
	v_lshlrev_b32_e32 v80, 1, v230
	s_addc_u32 s45, s1, s43
	v_and_b32_e32 v216, 0xffffffe0, v80
	v_lshl_add_u64 v[120:121], s[44:45], 0, v[216:217]
	s_movk_i32 s17, 0x5000
	v_add_co_u32_e32 v98, vcc, s17, v120
	global_load_dwordx4 v[80:83], v216, s[44:45] offset:16
	global_load_dwordx4 v[168:171], v216, s[44:45]
	s_mov_b64 s[44:45], 0x5800
	v_addc_co_u32_e32 v99, vcc, 0, v121, vcc
	s_mov_b32 s17, 0xb000
	s_add_u32 s42, s4, s42
	v_lshl_add_u64 v[96:97], v[120:121], 0, s[44:45]
	s_mov_b64 s[44:45], 0xb000
	v_add_co_u32_e32 v106, vcc, s17, v120
	s_addc_u32 s43, s5, s43
	v_lshl_add_u64 v[104:105], v[120:121], 0, s[44:45]
	v_addc_co_u32_e32 v107, vcc, 0, v121, vcc
	global_load_dwordx4 v[172:175], v[98:99], off offset:2048
	s_nop 0
	global_load_dwordx4 v[96:99], v[96:97], off offset:16
	s_nop 0
	global_load_dwordx4 v[176:179], v[106:107], off
	s_nop 0
	global_load_dwordx4 v[104:107], v[104:105], off offset:16
	s_nop 0
	global_load_dwordx4 v[108:111], v216, s[42:43] offset:16
	global_load_dwordx4 v[184:187], v216, s[42:43]
	v_add_co_u32_e32 v114, vcc, s88, v120
	s_mov_b32 s17, 0x8000
	s_nop 0
	v_addc_co_u32_e32 v115, vcc, 0, v121, vcc
	v_lshl_add_u64 v[124:125], s[42:43], 0, v[216:217]
	s_mov_b64 s[42:43], 0x8400
	v_add_co_u32_e32 v118, vcc, s17, v120
	v_lshl_add_u64 v[116:117], v[120:121], 0, s[42:43]
	s_nop 0
	v_addc_co_u32_e32 v119, vcc, 0, v121, vcc
	s_mov_b64 s[42:43], 0xdc00
	s_mov_b32 s17, 0xd000
	v_lshl_add_u64 v[112:113], v[120:121], 0, s[68:69]
	v_lshl_add_u64 v[122:123], v[120:121], 0, s[42:43]
	v_add_co_u32_e32 v120, vcc, s17, v120
	v_lshl_add_u64 v[126:127], v[124:125], 0, s[68:69]
	s_nop 0
	v_addc_co_u32_e32 v121, vcc, 0, v121, vcc
	v_add_co_u32_e32 v124, vcc, s88, v124
	global_load_dwordx4 v[180:183], v[114:115], off offset:3072
	s_nop 0
	global_load_dwordx4 v[112:115], v[112:113], off offset:16
	v_addc_co_u32_e32 v125, vcc, 0, v125, vcc
	global_load_dwordx4 v[188:191], v[118:119], off offset:1024
	s_nop 0
	global_load_dwordx4 v[116:119], v[116:117], off offset:16
	s_nop 0
	global_load_dwordx4 v[192:195], v[120:121], off offset:3072
	s_nop 0
	global_load_dwordx4 v[120:123], v[122:123], off offset:16
	s_nop 0
	global_load_dwordx4 v[196:199], v[124:125], off offset:3072
	s_nop 0
	global_load_dwordx4 v[124:127], v[126:127], off offset:16
	v_mov_b32_dpp v160, v136 row_shr:1 row_mask:0xf bank_mask:0xf bound_ctrl:1
	v_mov_b32_dpp v161, v137 row_shr:1 row_mask:0xf bank_mask:0xf bound_ctrl:1
	v_mov_b32_dpp v204, v156 row_shl:1 row_mask:0xf bank_mask:0xf bound_ctrl:1
	v_mov_b32_dpp v205, v157 row_shl:1 row_mask:0xf bank_mask:0xf bound_ctrl:1
	s_mov_b64 s[44:45], -1
	s_waitcnt vmcnt(0)
	v_pk_fma_f32 v[160:161], v[168:169], v[160:161], v[184:185]
	v_pk_fma_f32 v[160:161], v[156:157], v[172:173], v[160:161]
	v_pk_fma_f32 v[166:167], v[148:149], v[176:177], v[160:161]
	v_pk_fma_f32 v[160:161], v[156:157], v[168:169], v[184:185]
	v_pk_fma_f32 v[160:161], v[148:149], v[172:173], v[160:161]
	v_pk_fma_f32 v[164:165], v[152:153], v[176:177], v[160:161]
	v_pk_fma_f32 v[160:161], v[148:149], v[168:169], v[184:185]
	v_pk_fma_f32 v[160:161], v[152:153], v[172:173], v[160:161]
	v_pk_fma_f32 v[162:163], v[136:137], v[176:177], v[160:161]
	v_pk_fma_f32 v[160:161], v[152:153], v[168:169], v[184:185]
	v_pk_fma_f32 v[160:161], v[136:137], v[172:173], v[160:161]
	v_pk_fma_f32 v[160:161], v[176:177], v[204:205], v[160:161]
	v_mov_b32_dpp v204, v138 row_shr:1 row_mask:0xf bank_mask:0xf bound_ctrl:1
	v_mov_b32_dpp v205, v139 row_shr:1 row_mask:0xf bank_mask:0xf bound_ctrl:1
	v_mov_b32_dpp v208, v158 row_shl:1 row_mask:0xf bank_mask:0xf bound_ctrl:1
	v_mov_b32_dpp v209, v159 row_shl:1 row_mask:0xf bank_mask:0xf bound_ctrl:1
	v_pk_fma_f32 v[204:205], v[170:171], v[204:205], v[186:187]
	v_pk_fma_f32 v[204:205], v[158:159], v[174:175], v[204:205]
	v_pk_fma_f32 v[218:219], v[150:151], v[178:179], v[204:205]
	v_pk_fma_f32 v[204:205], v[158:159], v[170:171], v[186:187]
	v_pk_fma_f32 v[204:205], v[150:151], v[174:175], v[204:205]
	v_pk_fma_f32 v[212:213], v[154:155], v[178:179], v[204:205]
	v_pk_fma_f32 v[204:205], v[150:151], v[170:171], v[186:187]
	v_pk_fma_f32 v[204:205], v[154:155], v[174:175], v[204:205]
	v_pk_fma_f32 v[206:207], v[138:139], v[178:179], v[204:205]
	v_pk_fma_f32 v[204:205], v[154:155], v[170:171], v[186:187]
	v_pk_fma_f32 v[204:205], v[138:139], v[174:175], v[204:205]
	v_pk_fma_f32 v[204:205], v[178:179], v[208:209], v[204:205]
	v_mov_b32_dpp v208, v132 row_shr:1 row_mask:0xf bank_mask:0xf bound_ctrl:1
	v_mov_b32_dpp v209, v133 row_shr:1 row_mask:0xf bank_mask:0xf bound_ctrl:1
	v_mov_b32_dpp v210, v144 row_shl:1 row_mask:0xf bank_mask:0xf bound_ctrl:1
	v_mov_b32_dpp v211, v145 row_shl:1 row_mask:0xf bank_mask:0xf bound_ctrl:1
	v_pk_fma_f32 v[208:209], v[180:181], v[208:209], v[196:197]
	v_pk_fma_f32 v[208:209], v[144:145], v[188:189], v[208:209]
	v_pk_fma_f32 v[220:221], v[128:129], v[192:193], v[208:209]
	v_pk_fma_f32 v[208:209], v[144:145], v[180:181], v[196:197]
	v_pk_fma_f32 v[208:209], v[128:129], v[188:189], v[208:209]
	v_pk_fma_f32 v[222:223], v[140:141], v[192:193], v[208:209]
	v_pk_fma_f32 v[208:209], v[128:129], v[180:181], v[196:197]
	v_pk_fma_f32 v[208:209], v[140:141], v[188:189], v[208:209]
	v_pk_fma_f32 v[226:227], v[132:133], v[192:193], v[208:209]
	v_pk_fma_f32 v[208:209], v[140:141], v[180:181], v[196:197]
	v_pk_fma_f32 v[208:209], v[132:133], v[188:189], v[208:209]
	v_pk_fma_f32 v[210:211], v[192:193], v[210:211], v[208:209]
; __device__ __forceinline__ unsigned cvt_pk_f16(float lo, float hi) { unsigned r; asm volatile("v_cvt_pk_f16_f32 %0, %1, %2" : "=v"(r) : "v"(lo), "v"(hi)); return r; }
; __device__ __forceinline__ unsigned cvt_pk_bf16(float lo, float hi) { unsigned r; asm volatile("v_cvt_pk_bf16_f32 %0, %1, %2" : "=v"(r) : "v"(lo), "v"(hi)); return r; }
;     static __device__ __forceinline__ unsigned silu_pk(const f32x2 g, const f32x2 v) {
;         const f32x2 t = g * -1.4426950408889634f;
;         const f32x2 d = (f32x2){__builtin_amdgcn_exp2f(t.x), __builtin_amdgcn_exp2f(t.y)} + 1.0f;
;         const f32x2 o = g * v * (f32x2){__builtin_amdgcn_rcpf(d.x), __builtin_amdgcn_rcpf(d.y)};
;         return cvt_pk_bf16(o.x, o.y);
;     }
;     __device__ __forceinline__ void operator()(f32x4 (&acc)[2][2][4][2], const Unit& u, int wr, int wc, int lane) const {
;     ...
; #pragma unroll
;                 for (int m = 0; m < 4; ++m) {
;                     u32x2 w; w.x = silu_pk(hg[m][0], hv[m][0]); w.y = silu_pk(hg[m][1], hv[m][1]);
;                     if (n == 0) keep[ai][m] = w;
;                     else { u32x4 w4; w4.x = keep[ai][m].x; w4.y = keep[ai][m].y; w4.z = w.x; w4.w = w.y; gst<u32x4>(gu, ((unsigned)(4 * fr + m) * DFF + 8u * fq) * 2u, w4); }
;                 }
;                 if (fr == 0 || fr == 15) {
;                     const int mb = fr == 0 ? 0 : 2;
; #pragma unroll
;                     for (int e = 0; e < 2; ++e) { const unsigned eo = ((unsigned)(mb + e) * NUP + 8u * fq + 4u * n) * 2u;
;                         const f32x4 eg = fr == 0 ? acc[ai][0][e][n] : acc[ai][0][2 + e][n], ev = fr == 0 ? acc[ai][1][e][n] : acc[ai][1][2 + e][n];
;                         gst<u32x2>(eu, eo, (u32x2){cvt_pk_f16(eg[0], eg[1]), cvt_pk_f16(eg[2], eg[3])}); gst<u32x2>(eu + DFF, eo, (u32x2){cvt_pk_f16(ev[0], ev[1]), cvt_pk_f16(ev[2], ev[3])}); }
	v_mov_b32_dpp v208, v134 row_shr:1 row_mask:0xf bank_mask:0xf bound_ctrl:1
	v_mov_b32_dpp v209, v135 row_shr:1 row_mask:0xf bank_mask:0xf bound_ctrl:1
	v_mov_b32_dpp v228, v146 row_shl:1 row_mask:0xf bank_mask:0xf bound_ctrl:1
	v_mov_b32_dpp v229, v147 row_shl:1 row_mask:0xf bank_mask:0xf bound_ctrl:1
	v_pk_fma_f32 v[208:209], v[182:183], v[208:209], v[198:199]
	v_pk_fma_f32 v[208:209], v[146:147], v[190:191], v[208:209]
	v_pk_fma_f32 v[236:237], v[130:131], v[194:195], v[208:209]
	v_pk_fma_f32 v[208:209], v[146:147], v[182:183], v[198:199]
	v_pk_fma_f32 v[208:209], v[130:131], v[190:191], v[208:209]
	v_pk_fma_f32 v[238:239], v[142:143], v[194:195], v[208:209]
	v_pk_fma_f32 v[208:209], v[130:131], v[182:183], v[198:199]
	v_pk_fma_f32 v[208:209], v[142:143], v[190:191], v[208:209]
	v_pk_fma_f32 v[240:241], v[134:135], v[194:195], v[208:209]
	v_pk_fma_f32 v[208:209], v[142:143], v[182:183], v[198:199]
	v_pk_fma_f32 v[208:209], v[134:135], v[190:191], v[208:209]
	v_pk_fma_f32 v[208:209], v[194:195], v[228:229], v[208:209]
	v_pk_mul_f32 v[228:229], v[166:167], s[12:13] op_sel_hi:[1,0]
	v_exp_f32_e32 v228, v228
	v_exp_f32_e32 v229, v229
	v_pk_mul_f32 v[166:167], v[166:167], v[220:221]
	v_pk_add_f32 v[228:229], v[228:229], 1.0 op_sel_hi:[1,0]
	v_rcp_f32_e32 v220, v228
	v_rcp_f32_e32 v221, v229
	s_nop 0
	v_pk_mul_f32 v[166:167], v[166:167], v[220:221]
	v_pk_mul_f32 v[220:221], v[218:219], s[12:13] op_sel_hi:[1,0]
	v_pk_mul_f32 v[218:219], v[218:219], v[236:237]
	v_exp_f32_e32 v220, v220
	v_exp_f32_e32 v221, v221
	v_cvt_pk_bf16_f32 v166, v166, v167
	v_pk_add_f32 v[220:221], v[220:221], 1.0 op_sel_hi:[1,0]
	v_rcp_f32_e32 v220, v220
	v_rcp_f32_e32 v221, v221
	s_nop 0
	v_pk_mul_f32 v[218:219], v[218:219], v[220:221]
	v_cvt_pk_bf16_f32 v167, v218, v219
	v_pk_mul_f32 v[218:219], v[164:165], s[12:13] op_sel_hi:[1,0]
	v_exp_f32_e32 v218, v218
	v_exp_f32_e32 v219, v219
	v_pk_mul_f32 v[164:165], v[164:165], v[222:223]
	v_pk_add_f32 v[218:219], v[218:219], 1.0 op_sel_hi:[1,0]
	v_rcp_f32_e32 v218, v218
	v_rcp_f32_e32 v219, v219
	s_nop 0
	v_pk_mul_f32 v[164:165], v[164:165], v[218:219]
	v_pk_mul_f32 v[218:219], v[212:213], s[12:13] op_sel_hi:[1,0]
	v_pk_mul_f32 v[212:213], v[212:213], v[238:239]
	v_exp_f32_e32 v218, v218
	v_exp_f32_e32 v219, v219
	v_cvt_pk_bf16_f32 v164, v164, v165
	v_pk_add_f32 v[218:219], v[218:219], 1.0 op_sel_hi:[1,0]
	v_rcp_f32_e32 v218, v218
	v_rcp_f32_e32 v219, v219
	s_nop 0
	v_pk_mul_f32 v[212:213], v[212:213], v[218:219]
	v_cvt_pk_bf16_f32 v165, v212, v213
	v_pk_mul_f32 v[212:213], v[162:163], s[12:13] op_sel_hi:[1,0]
	v_exp_f32_e32 v212, v212
	v_exp_f32_e32 v213, v213
	v_pk_mul_f32 v[162:163], v[162:163], v[226:227]
	v_pk_add_f32 v[212:213], v[212:213], 1.0 op_sel_hi:[1,0]
	v_rcp_f32_e32 v212, v212
	v_rcp_f32_e32 v213, v213
	s_nop 0
	v_pk_mul_f32 v[162:163], v[162:163], v[212:213]
	v_pk_mul_f32 v[212:213], v[206:207], s[12:13] op_sel_hi:[1,0]
	v_pk_mul_f32 v[206:207], v[206:207], v[240:241]
	v_exp_f32_e32 v212, v212
	v_exp_f32_e32 v213, v213
	v_cvt_pk_bf16_f32 v162, v162, v163
	v_pk_add_f32 v[212:213], v[212:213], 1.0 op_sel_hi:[1,0]
	v_rcp_f32_e32 v212, v212
	v_rcp_f32_e32 v213, v213
	s_nop 0
	v_pk_mul_f32 v[206:207], v[206:207], v[212:213]
	v_cvt_pk_bf16_f32 v163, v206, v207
	v_pk_mul_f32 v[206:207], v[160:161], s[12:13] op_sel_hi:[1,0]
	v_exp_f32_e32 v206, v206
	v_exp_f32_e32 v207, v207
	v_pk_mul_f32 v[160:161], v[160:161], v[210:211]
	v_pk_add_f32 v[206:207], v[206:207], 1.0 op_sel_hi:[1,0]
	v_rcp_f32_e32 v206, v206
	v_rcp_f32_e32 v207, v207
	s_nop 0
	v_pk_mul_f32 v[160:161], v[160:161], v[206:207]
	v_pk_mul_f32 v[206:207], v[204:205], s[12:13] op_sel_hi:[1,0]
	v_pk_mul_f32 v[204:205], v[204:205], v[208:209]
	v_exp_f32_e32 v206, v206
	v_exp_f32_e32 v207, v207
	v_cvt_pk_bf16_f32 v160, v160, v161
	v_pk_add_f32 v[206:207], v[206:207], 1.0 op_sel_hi:[1,0]
	v_rcp_f32_e32 v206, v206
	v_rcp_f32_e32 v207, v207
	s_nop 0
	v_pk_mul_f32 v[204:205], v[204:205], v[206:207]
	v_cvt_pk_bf16_f32 v161, v204, v205
	v_and_b32_e32 v204, 15, v230
	v_cmp_eq_u32_e32 vcc, 0, v204
	v_cmp_gt_i32_e64 s[42:43], 15, v204
	s_and_saveexec_b64 s[52:53], s[42:43]
	v_cmp_eq_u32_e64 s[42:43], 0, v204
	s_orn2_b64 s[44:45], s[42:43], exec
	s_or_b64 exec, exec, s[52:53]
	s_lshl_b32 s17, s60, 2
	s_add_i32 s17, s17, s18
	v_and_b32_e32 v205, -16, v230
	v_cndmask_b32_e64 v206, 2, 0, vcc
	s_mul_hi_i32 s61, s17, 0xb000
	s_mul_i32 s62, s17, 0xb000
	v_mad_u32_u24 v207, v206, s89, v205
	s_and_saveexec_b64 s[42:43], s[44:45]
	s_cbranch_execz .LBB0_138
	s_add_u32 s21, s34, s62
	s_addc_u32 s52, s35, s61
	s_lshl_b64 s[44:45], s[48:49], 1
	s_add_u32 s44, s21, s44
	s_addc_u32 s45, s52, s45
	s_add_u32 s52, s44, 0x1600
	v_cndmask_b32_e32 v152, v152, v156, vcc
	v_cndmask_b32_e32 v153, v153, v157, vcc
	v_cndmask_b32_e32 v144, v140, v144, vcc
	v_cvt_pk_f16_f32 v140, v152, v153
	s_addc_u32 s53, s45, 0
	v_cndmask_b32_e32 v154, v154, v158, vcc
	v_cndmask_b32_e32 v155, v155, v159, vcc
	v_cndmask_b32_e32 v145, v141, v145, vcc
	v_cvt_pk_f16_f32 v141, v154, v155
	global_store_dwordx2 v207, v[140:141], s[44:45]
	v_cvt_pk_f16_f32 v140, v144, v145
	v_cndmask_b32_e32 v142, v142, v146, vcc
	v_cndmask_b32_e32 v143, v143, v147, vcc
	v_cvt_pk_f16_f32 v141, v142, v143
	global_store_dwordx2 v207, v[140:141], s[52:53]
	v_add_u32_e32 v140, 0x2c00, v207
	v_cndmask_b32_e32 v138, v138, v150, vcc
	v_cndmask_b32_e32 v139, v139, v151, vcc
	v_cndmask_b32_e32 v136, v136, v148, vcc
	v_cndmask_b32_e32 v137, v137, v149, vcc
	v_cndmask_b32_e32 v132, v132, v128, vcc
	v_cndmask_b32_e32 v133, v133, v129, vcc
	v_cvt_pk_f16_f32 v128, v136, v137
	v_cvt_pk_f16_f32 v129, v138, v139
	v_cndmask_b32_e32 v130, v134, v130, vcc
	v_cndmask_b32_e32 v131, v135, v131, vcc
	global_store_dwordx2 v140, v[128:129], s[44:45]
	v_cvt_pk_f16_f32 v128, v132, v133
	v_cvt_pk_f16_f32 v129, v130, v131
	global_store_dwordx2 v140, v[128:129], s[52:53]
;     __device__ __forceinline__ void conv4(const f32x4& a0, const f32x4& a1, const f32x4& a2, const f32x4& a3, const f32x4& w0, const f32x4& w1, const f32x4& w2, const f32x4& b, f32x2 (&h)[4][2]) const {
; #pragma unroll
;         for (int p = 0; p < 2; ++p) {
;             float u0, u1, d0, d1;
;             asm volatile("s_nop 1\n\tv_mov_b32_dpp %0, %1 row_shr:1 row_mask:0xf bank_mask:0xf bound_ctrl:1" : "=&v"(u0) : "v"(a3[2 * p]));
;             asm volatile("s_nop 1\n\tv_mov_b32_dpp %0, %1 row_shr:1 row_mask:0xf bank_mask:0xf bound_ctrl:1" : "=&v"(u1) : "v"(a3[2 * p + 1]));
;             asm volatile("s_nop 1\n\tv_mov_b32_dpp %0, %1 row_shl:1 row_mask:0xf bank_mask:0xf bound_ctrl:1" : "=&v"(d0) : "v"(a0[2 * p]));
;             asm volatile("s_nop 1\n\tv_mov_b32_dpp %0, %1 row_shl:1 row_mask:0xf bank_mask:0xf bound_ctrl:1" : "=&v"(d1) : "v"(a0[2 * p + 1]));
;             const f32x2 UP = {u0, u1}, DN = {d0, d1};
;             const f32x2 A0 = {a0[2 * p], a0[2 * p + 1]}, A1 = {a1[2 * p], a1[2 * p + 1]}, A2 = {a2[2 * p], a2[2 * p + 1]}, A3 = {a3[2 * p], a3[2 * p + 1]};
;             const f32x2 W0 = {w0[2 * p], w0[2 * p + 1]}, W1 = {w1[2 * p], w1[2 * p + 1]}, W2 = {w2[2 * p], w2[2 * p + 1]}, B = {b[2 * p], b[2 * p + 1]};
;             h[0][p] = B + W0 * UP + W1 * A0 + W2 * A1;
;             h[1][p] = B + W0 * A0 + W1 * A1 + W2 * A2;
;             h[2][p] = B + W0 * A1 + W1 * A2 + W2 * A3;
;             h[3][p] = B + W0 * A2 + W1 * A3 + W2 * DN;
;         }
;     }
.LBB0_138:
	s_or_b64 exec, exec, s[42:43]
	v_mov_b32_dpp v128, v68 row_shr:1 row_mask:0xf bank_mask:0xf bound_ctrl:1
	v_mov_b32_dpp v129, v69 row_shr:1 row_mask:0xf bank_mask:0xf bound_ctrl:1
	v_pk_fma_f32 v[138:139], v[102:103], v[170:171], v[186:187]
	v_pk_fma_f32 v[128:129], v[168:169], v[128:129], v[184:185]
	v_pk_fma_f32 v[138:139], v[66:67], v[174:175], v[138:139]
	v_pk_fma_f32 v[128:129], v[100:101], v[172:173], v[128:129]
	v_pk_fma_f32 v[146:147], v[94:95], v[178:179], v[138:139]
	v_pk_fma_f32 v[134:135], v[64:65], v[176:177], v[128:129]
	v_pk_fma_f32 v[128:129], v[100:101], v[168:169], v[184:185]
	v_pk_fma_f32 v[138:139], v[66:67], v[170:171], v[186:187]
	v_pk_fma_f32 v[128:129], v[64:65], v[172:173], v[128:129]
	v_pk_fma_f32 v[138:139], v[94:95], v[174:175], v[138:139]
	v_pk_fma_f32 v[144:145], v[92:93], v[176:177], v[128:129]
	v_pk_fma_f32 v[128:129], v[64:65], v[168:169], v[184:185]
	v_mov_b32_dpp v132, v100 row_shl:1 row_mask:0xf bank_mask:0xf bound_ctrl:1
	v_mov_b32_dpp v133, v101 row_shl:1 row_mask:0xf bank_mask:0xf bound_ctrl:1
	v_pk_fma_f32 v[142:143], v[70:71], v[178:179], v[138:139]
	v_pk_fma_f32 v[128:129], v[92:93], v[172:173], v[128:129]
	v_pk_fma_f32 v[138:139], v[94:95], v[170:171], v[186:187]
	v_pk_fma_f32 v[130:131], v[68:69], v[176:177], v[128:129]
	v_pk_fma_f32 v[128:129], v[92:93], v[168:169], v[184:185]
	v_pk_fma_f32 v[138:139], v[70:71], v[174:175], v[138:139]
	v_pk_fma_f32 v[128:129], v[68:69], v[172:173], v[128:129]
	v_cmp_gt_i32_e64 s[42:43], 15, v204
	v_pk_fma_f32 v[128:129], v[176:177], v[132:133], v[128:129]
	v_mov_b32_dpp v132, v70 row_shr:1 row_mask:0xf bank_mask:0xf bound_ctrl:1
	v_mov_b32_dpp v133, v71 row_shr:1 row_mask:0xf bank_mask:0xf bound_ctrl:1
	v_mov_b32_dpp v136, v102 row_shl:1 row_mask:0xf bank_mask:0xf bound_ctrl:1
	v_mov_b32_dpp v137, v103 row_shl:1 row_mask:0xf bank_mask:0xf bound_ctrl:1
	s_mov_b64 s[44:45], -1
	v_pk_fma_f32 v[136:137], v[178:179], v[136:137], v[138:139]
	v_mov_b32_dpp v138, v76 row_shr:1 row_mask:0xf bank_mask:0xf bound_ctrl:1
	v_mov_b32_dpp v139, v77 row_shr:1 row_mask:0xf bank_mask:0xf bound_ctrl:1
	v_mov_b32_dpp v140, v88 row_shl:1 row_mask:0xf bank_mask:0xf bound_ctrl:1
	v_mov_b32_dpp v141, v89 row_shl:1 row_mask:0xf bank_mask:0xf bound_ctrl:1
	v_pk_fma_f32 v[132:133], v[170:171], v[132:133], v[186:187]
	v_pk_fma_f32 v[138:139], v[180:181], v[138:139], v[196:197]
	v_pk_fma_f32 v[132:133], v[102:103], v[174:175], v[132:133]
	v_pk_fma_f32 v[138:139], v[88:89], v[188:189], v[138:139]
	v_pk_fma_f32 v[132:133], v[66:67], v[178:179], v[132:133]
	v_pk_fma_f32 v[148:149], v[72:73], v[192:193], v[138:139]
	v_pk_fma_f32 v[138:139], v[88:89], v[180:181], v[196:197]
	v_pk_fma_f32 v[138:139], v[72:73], v[188:189], v[138:139]
	v_pk_fma_f32 v[150:151], v[84:85], v[192:193], v[138:139]
	v_pk_fma_f32 v[138:139], v[72:73], v[180:181], v[196:197]
	v_pk_fma_f32 v[138:139], v[84:85], v[188:189], v[138:139]
	v_pk_fma_f32 v[152:153], v[76:77], v[192:193], v[138:139]
	v_pk_fma_f32 v[138:139], v[84:85], v[180:181], v[196:197]
	v_pk_fma_f32 v[138:139], v[76:77], v[188:189], v[138:139]
	v_pk_fma_f32 v[140:141], v[192:193], v[140:141], v[138:139]
	v_mov_b32_dpp v138, v78 row_shr:1 row_mask:0xf bank_mask:0xf bound_ctrl:1
	v_mov_b32_dpp v139, v79 row_shr:1 row_mask:0xf bank_mask:0xf bound_ctrl:1
	v_mov_b32_dpp v154, v90 row_shl:1 row_mask:0xf bank_mask:0xf bound_ctrl:1
	v_mov_b32_dpp v155, v91 row_shl:1 row_mask:0xf bank_mask:0xf bound_ctrl:1
	v_pk_fma_f32 v[138:139], v[182:183], v[138:139], v[198:199]
	v_pk_fma_f32 v[138:139], v[90:91], v[190:191], v[138:139]
	v_pk_fma_f32 v[156:157], v[74:75], v[194:195], v[138:139]
	v_pk_fma_f32 v[138:139], v[90:91], v[182:183], v[198:199]
; __device__ __forceinline__ unsigned cvt_pk_bf16(float lo, float hi) { unsigned r; asm volatile("v_cvt_pk_bf16_f32 %0, %1, %2" : "=v"(r) : "v"(lo), "v"(hi)); return r; }
;     static __device__ __forceinline__ unsigned silu_pk(const f32x2 g, const f32x2 v) {
;         const f32x2 t = g * -1.4426950408889634f;
;         const f32x2 d = (f32x2){__builtin_amdgcn_exp2f(t.x), __builtin_amdgcn_exp2f(t.y)} + 1.0f;
;         const f32x2 o = g * v * (f32x2){__builtin_amdgcn_rcpf(d.x), __builtin_amdgcn_rcpf(d.y)};
;         return cvt_pk_bf16(o.x, o.y);
;     }
;     __device__ __forceinline__ void operator()(f32x4 (&acc)[2][2][4][2], const Unit& u, int wr, int wc, int lane) const {
;     ...
; #pragma unroll
;                 for (int m = 0; m < 4; ++m) {
;                     u32x2 w; w.x = silu_pk(hg[m][0], hv[m][0]); w.y = silu_pk(hg[m][1], hv[m][1]);
;                     if (n == 0) keep[ai][m] = w;
;                     else { u32x4 w4; w4.x = keep[ai][m].x; w4.y = keep[ai][m].y; w4.z = w.x; w4.w = w.y; gst<u32x4>(gu, ((unsigned)(4 * fr + m) * DFF + 8u * fq) * 2u, w4); }
;                 }
;                 if (fr == 0 || fr == 15) {
;                     const int mb = fr == 0 ? 0 : 2;
	v_pk_fma_f32 v[138:139], v[74:75], v[190:191], v[138:139]
	v_pk_fma_f32 v[158:159], v[86:87], v[194:195], v[138:139]
	v_pk_fma_f32 v[138:139], v[74:75], v[182:183], v[198:199]
	v_pk_fma_f32 v[138:139], v[86:87], v[190:191], v[138:139]
	v_pk_fma_f32 v[168:169], v[78:79], v[194:195], v[138:139]
	v_pk_fma_f32 v[138:139], v[86:87], v[182:183], v[198:199]
	v_pk_fma_f32 v[138:139], v[78:79], v[190:191], v[138:139]
	v_pk_fma_f32 v[138:139], v[194:195], v[154:155], v[138:139]
	v_pk_mul_f32 v[154:155], v[134:135], s[12:13] op_sel_hi:[1,0]
	v_exp_f32_e32 v154, v154
	v_exp_f32_e32 v155, v155
	v_pk_mul_f32 v[134:135], v[134:135], v[148:149]
	v_pk_add_f32 v[154:155], v[154:155], 1.0 op_sel_hi:[1,0]
	v_rcp_f32_e32 v148, v154
	v_rcp_f32_e32 v149, v155
	s_nop 0
	v_pk_mul_f32 v[134:135], v[134:135], v[148:149]
	v_pk_mul_f32 v[148:149], v[132:133], s[12:13] op_sel_hi:[1,0]
	v_pk_mul_f32 v[132:133], v[132:133], v[156:157]
	v_exp_f32_e32 v148, v148
	v_exp_f32_e32 v149, v149
	v_cvt_pk_bf16_f32 v134, v134, v135
	v_pk_add_f32 v[148:149], v[148:149], 1.0 op_sel_hi:[1,0]
	v_rcp_f32_e32 v148, v148
	v_rcp_f32_e32 v149, v149
	s_nop 0
	v_pk_mul_f32 v[132:133], v[132:133], v[148:149]
	v_cvt_pk_bf16_f32 v135, v132, v133
	v_pk_mul_f32 v[132:133], v[144:145], s[12:13] op_sel_hi:[1,0]
	v_exp_f32_e32 v132, v132
	v_exp_f32_e32 v133, v133
	v_pk_mul_f32 v[144:145], v[144:145], v[150:151]
	v_pk_add_f32 v[132:133], v[132:133], 1.0 op_sel_hi:[1,0]
	v_rcp_f32_e32 v132, v132
	v_rcp_f32_e32 v133, v133
	s_nop 0
	v_pk_mul_f32 v[132:133], v[144:145], v[132:133]
	v_pk_mul_f32 v[144:145], v[146:147], s[12:13] op_sel_hi:[1,0]
	v_pk_mul_f32 v[146:147], v[146:147], v[158:159]
	v_exp_f32_e32 v144, v144
	v_exp_f32_e32 v145, v145
	v_cvt_pk_bf16_f32 v132, v132, v133
	v_pk_add_f32 v[144:145], v[144:145], 1.0 op_sel_hi:[1,0]
	v_rcp_f32_e32 v144, v144
	v_rcp_f32_e32 v145, v145
	s_nop 0
	v_pk_mul_f32 v[144:145], v[146:147], v[144:145]
	v_cvt_pk_bf16_f32 v133, v144, v145
	v_pk_mul_f32 v[144:145], v[130:131], s[12:13] op_sel_hi:[1,0]
	v_exp_f32_e32 v144, v144
	v_exp_f32_e32 v145, v145
	v_pk_mul_f32 v[130:131], v[130:131], v[152:153]
	v_pk_add_f32 v[144:145], v[144:145], 1.0 op_sel_hi:[1,0]
	v_rcp_f32_e32 v144, v144
	v_rcp_f32_e32 v145, v145
	s_nop 0
	v_pk_mul_f32 v[130:131], v[130:131], v[144:145]
	v_pk_mul_f32 v[144:145], v[142:143], s[12:13] op_sel_hi:[1,0]
	v_pk_mul_f32 v[142:143], v[142:143], v[168:169]
	v_exp_f32_e32 v144, v144
	v_exp_f32_e32 v145, v145
	v_cvt_pk_bf16_f32 v130, v130, v131
	v_pk_add_f32 v[144:145], v[144:145], 1.0 op_sel_hi:[1,0]
	v_rcp_f32_e32 v144, v144
	v_rcp_f32_e32 v145, v145
	s_nop 0
	v_pk_mul_f32 v[142:143], v[142:143], v[144:145]
	v_cvt_pk_bf16_f32 v131, v142, v143
	v_pk_mul_f32 v[142:143], v[128:129], s[12:13] op_sel_hi:[1,0]
	v_exp_f32_e32 v142, v142
	v_exp_f32_e32 v143, v143
	v_pk_mul_f32 v[128:129], v[128:129], v[140:141]
	v_pk_add_f32 v[142:143], v[142:143], 1.0 op_sel_hi:[1,0]
	v_rcp_f32_e32 v140, v142
	v_rcp_f32_e32 v141, v143
	s_nop 0
	v_pk_mul_f32 v[128:129], v[128:129], v[140:141]
	v_pk_mul_f32 v[140:141], v[136:137], s[12:13] op_sel_hi:[1,0]
	v_pk_mul_f32 v[136:137], v[136:137], v[138:139]
	v_exp_f32_e32 v140, v140
	v_exp_f32_e32 v141, v141
	v_cvt_pk_bf16_f32 v128, v128, v129
	v_pk_add_f32 v[140:141], v[140:141], 1.0 op_sel_hi:[1,0]
	v_rcp_f32_e32 v138, v140
	v_rcp_f32_e32 v139, v141
	s_nop 0
	v_pk_mul_f32 v[136:137], v[136:137], v[138:139]
	v_cvt_pk_bf16_f32 v129, v136, v137
	s_and_saveexec_b64 s[52:53], s[42:43]
	s_cbranch_execz .LBB0_142
	v_cmp_eq_u32_e64 s[42:43], 0, v204
	v_cmp_ne_u32_e64 s[44:45], 0, v204
	s_and_saveexec_b64 s[56:57], s[44:45]
	v_add_u32_e32 v136, 0x2c00, v205
	s_or_b64 exec, exec, s[56:57]
	s_orn2_b64 s[44:45], s[42:43], exec

; #define GAS __attribute__((address_space(1)))
;     __device__ __forceinline__ void conv4(const f32x4& a0, const f32x4& a1, const f32x4& a2, const f32x4& a3, const f32x4& w0, const f32x4& w1, const f32x4& w2, const f32x4& b, f32x2 (&h)[4][2]) const {
; #pragma unroll
;         for (int p = 0; p < 2; ++p) {
;             float u0, u1, d0, d1;
;             asm volatile("s_nop 1\n\tv_mov_b32_dpp %0, %1 row_shr:1 row_mask:0xf bank_mask:0xf bound_ctrl:1" : "=&v"(u0) : "v"(a3[2 * p]));
;             asm volatile("s_nop 1\n\tv_mov_b32_dpp %0, %1 row_shr:1 row_mask:0xf bank_mask:0xf bound_ctrl:1" : "=&v"(u1) : "v"(a3[2 * p + 1]));
;             asm volatile("s_nop 1\n\tv_mov_b32_dpp %0, %1 row_shl:1 row_mask:0xf bank_mask:0xf bound_ctrl:1" : "=&v"(d0) : "v"(a0[2 * p]));
;             asm volatile("s_nop 1\n\tv_mov_b32_dpp %0, %1 row_shl:1 row_mask:0xf bank_mask:0xf bound_ctrl:1" : "=&v"(d1) : "v"(a0[2 * p + 1]));
;             const f32x2 UP = {u0, u1}, DN = {d0, d1};
;             const f32x2 A0 = {a0[2 * p], a0[2 * p + 1]}, A1 = {a1[2 * p], a1[2 * p + 1]}, A2 = {a2[2 * p], a2[2 * p + 1]}, A3 = {a3[2 * p], a3[2 * p + 1]};
;             const f32x2 W0 = {w0[2 * p], w0[2 * p + 1]}, W1 = {w1[2 * p], w1[2 * p + 1]}, W2 = {w2[2 * p], w2[2 * p + 1]}, B = {b[2 * p], b[2 * p + 1]};
;             h[0][p] = B + W0 * UP + W1 * A0 + W2 * A1;
;             h[1][p] = B + W0 * A0 + W1 * A1 + W2 * A2;
;             h[2][p] = B + W0 * A1 + W1 * A2 + W2 * A3;
;             h[3][p] = B + W0 * A2 + W1 * A3 + W2 * DN;
;         }
;     }
;     static __device__ __forceinline__ unsigned silu_pk(const f32x2 g, const f32x2 v) {
;         const f32x2 t = g * -1.4426950408889634f;
;         const f32x2 d = (f32x2){__builtin_amdgcn_exp2f(t.x), __builtin_amdgcn_exp2f(t.y)} + 1.0f;
;         const f32x2 o = g * v * (f32x2){__builtin_amdgcn_rcpf(d.x), __builtin_amdgcn_rcpf(d.y)};
;         return cvt_pk_bf16(o.x, o.y);
;     }
;     __device__ __forceinline__ void operator()(f32x4 (&acc)[2][2][4][2], const Unit& u, int wr, int wc, int lane) const {
;         const int fr = lane & 15, fq = lane >> 4;
;         const int colu = u.pn * 128 + wc * 32;
;         const GAS float* cwu = cw + colu; const GAS float* cbu = cb + colu;
;         u32x2 keep[2][4];
;         f32x4 wgt[2][8];
; #pragma unroll
;         for (int n = 0; n < 2; ++n) { const unsigned co = (unsigned)(8 * fq + 4 * n) * 4u;
.LBB0_144:
	s_or_b64 exec, exec, s[42:43]
	v_pk_fma_f32 v[68:69], v[60:61], v[80:81], v[108:109]
	v_mov_b32_dpp v64, v48 row_shr:1 row_mask:0xf bank_mask:0xf bound_ctrl:1
	v_mov_b32_dpp v65, v49 row_shr:1 row_mask:0xf bank_mask:0xf bound_ctrl:1
	v_mov_b32_dpp v66, v60 row_shl:1 row_mask:0xf bank_mask:0xf bound_ctrl:1
	v_mov_b32_dpp v67, v61 row_shl:1 row_mask:0xf bank_mask:0xf bound_ctrl:1
	s_lshl_b32 s56, s60, 8
	v_pk_fma_f32 v[68:69], v[52:53], v[96:97], v[68:69]
	v_pk_fma_f32 v[64:65], v[80:81], v[64:65], v[108:109]
	v_pk_fma_f32 v[86:87], v[56:57], v[104:105], v[68:69]
	v_pk_fma_f32 v[68:69], v[52:53], v[80:81], v[108:109]
	v_pk_fma_f32 v[64:65], v[60:61], v[96:97], v[64:65]
	v_pk_fma_f32 v[68:69], v[56:57], v[96:97], v[68:69]
	v_pk_fma_f32 v[64:65], v[52:53], v[104:105], v[64:65]
	v_pk_fma_f32 v[76:77], v[48:49], v[104:105], v[68:69]
	v_pk_fma_f32 v[68:69], v[56:57], v[80:81], v[108:109]
	s_add_i32 s56, s56, s36
	v_pk_fma_f32 v[68:69], v[48:49], v[96:97], v[68:69]
	s_mul_i32 s43, s56, 0x1600
	v_pk_fma_f32 v[70:71], v[104:105], v[66:67], v[68:69]
	v_mov_b32_dpp v66, v50 row_shr:1 row_mask:0xf bank_mask:0xf bound_ctrl:1
	v_mov_b32_dpp v67, v51 row_shr:1 row_mask:0xf bank_mask:0xf bound_ctrl:1
	v_mov_b32_dpp v72, v62 row_shl:1 row_mask:0xf bank_mask:0xf bound_ctrl:1
	v_mov_b32_dpp v73, v63 row_shl:1 row_mask:0xf bank_mask:0xf bound_ctrl:1
	s_mul_hi_i32 s42, s56, 0x1600
	v_pk_fma_f32 v[66:67], v[82:83], v[66:67], v[110:111]
	s_add_u32 s43, s31, s43
	v_pk_fma_f32 v[66:67], v[62:63], v[98:99], v[66:67]
	s_addc_u32 s52, s33, s42
	v_pk_fma_f32 v[88:89], v[54:55], v[106:107], v[66:67]
	v_pk_fma_f32 v[66:67], v[62:63], v[82:83], v[110:111]
	s_lshl_b64 s[44:45], s[48:49], 1
	v_pk_fma_f32 v[66:67], v[54:55], v[98:99], v[66:67]
	s_add_u32 s42, s43, s44
	v_pk_fma_f32 v[90:91], v[58:59], v[106:107], v[66:67]
	v_pk_fma_f32 v[66:67], v[54:55], v[82:83], v[110:111]
	s_addc_u32 s43, s52, s45
	v_pk_fma_f32 v[66:67], v[58:59], v[98:99], v[66:67]
	v_mad_u32_u24 v216, v204, s92, v205
	v_pk_fma_f32 v[68:69], v[50:51], v[106:107], v[66:67]
	v_pk_fma_f32 v[66:67], v[58:59], v[82:83], v[110:111]
	s_mov_b64 s[48:49], -1
	v_pk_fma_f32 v[66:67], v[50:51], v[98:99], v[66:67]
	v_pk_fma_f32 v[66:67], v[106:107], v[72:73], v[66:67]
	v_mov_b32_dpp v72, v40 row_shr:1 row_mask:0xf bank_mask:0xf bound_ctrl:1
	v_mov_b32_dpp v73, v41 row_shr:1 row_mask:0xf bank_mask:0xf bound_ctrl:1
	v_mov_b32_dpp v74, v36 row_shl:1 row_mask:0xf bank_mask:0xf bound_ctrl:1
	v_mov_b32_dpp v75, v37 row_shl:1 row_mask:0xf bank_mask:0xf bound_ctrl:1
	v_pk_fma_f32 v[72:73], v[112:113], v[72:73], v[124:125]
	v_pk_fma_f32 v[72:73], v[36:37], v[116:117], v[72:73]
	v_pk_fma_f32 v[92:93], v[32:33], v[120:121], v[72:73]
	v_pk_fma_f32 v[72:73], v[36:37], v[112:113], v[124:125]
	v_pk_fma_f32 v[72:73], v[32:33], v[116:117], v[72:73]
	v_pk_fma_f32 v[94:95], v[44:45], v[120:121], v[72:73]
	v_pk_fma_f32 v[72:73], v[32:33], v[112:113], v[124:125]
	v_pk_fma_f32 v[72:73], v[44:45], v[116:117], v[72:73]
	v_pk_fma_f32 v[84:85], v[40:41], v[120:121], v[72:73]
	v_pk_fma_f32 v[72:73], v[44:45], v[112:113], v[124:125]
	v_pk_fma_f32 v[72:73], v[40:41], v[116:117], v[72:73]
	v_pk_fma_f32 v[74:75], v[120:121], v[74:75], v[72:73]
	v_mov_b32_dpp v72, v42 row_shr:1 row_mask:0xf bank_mask:0xf bound_ctrl:1
	v_mov_b32_dpp v73, v43 row_shr:1 row_mask:0xf bank_mask:0xf bound_ctrl:1
	v_mov_b32_dpp v100, v38 row_shl:1 row_mask:0xf bank_mask:0xf bound_ctrl:1
	v_mov_b32_dpp v101, v39 row_shl:1 row_mask:0xf bank_mask:0xf bound_ctrl:1
	v_pk_fma_f32 v[72:73], v[114:115], v[72:73], v[126:127]
	v_pk_fma_f32 v[72:73], v[38:39], v[118:119], v[72:73]
	v_pk_fma_f32 v[102:103], v[34:35], v[122:123], v[72:73]
	v_pk_fma_f32 v[72:73], v[38:39], v[114:115], v[126:127]
	v_pk_fma_f32 v[72:73], v[34:35], v[118:119], v[72:73]
	v_pk_fma_f32 v[138:139], v[46:47], v[122:123], v[72:73]
	v_pk_fma_f32 v[72:73], v[34:35], v[114:115], v[126:127]
	v_pk_fma_f32 v[72:73], v[46:47], v[118:119], v[72:73]
	v_pk_fma_f32 v[78:79], v[42:43], v[122:123], v[72:73]
	v_pk_fma_f32 v[72:73], v[46:47], v[114:115], v[126:127]
	v_pk_fma_f32 v[72:73], v[42:43], v[118:119], v[72:73]
	v_pk_fma_f32 v[72:73], v[122:123], v[100:101], v[72:73]
	v_pk_mul_f32 v[100:101], v[64:65], s[12:13] op_sel_hi:[1,0]
	v_exp_f32_e32 v100, v100
	v_exp_f32_e32 v101, v101
	v_pk_mul_f32 v[64:65], v[64:65], v[92:93]
	v_pk_add_f32 v[100:101], v[100:101], 1.0 op_sel_hi:[1,0]
	v_rcp_f32_e32 v92, v100
	v_rcp_f32_e32 v93, v101
	s_nop 0
	v_pk_mul_f32 v[64:65], v[64:65], v[92:93]
	v_cvt_pk_bf16_f32 v168, v64, v65
	v_pk_mul_f32 v[64:65], v[88:89], s[12:13] op_sel_hi:[1,0]
	v_exp_f32_e32 v64, v64
	v_exp_f32_e32 v65, v65
	v_pk_mul_f32 v[88:89], v[88:89], v[102:103]
	v_pk_add_f32 v[64:65], v[64:65], 1.0 op_sel_hi:[1,0]
	v_rcp_f32_e32 v64, v64
	v_rcp_f32_e32 v65, v65
	s_nop 0
	v_pk_mul_f32 v[64:65], v[88:89], v[64:65]
	v_cvt_pk_bf16_f32 v169, v64, v65
	v_pk_mul_f32 v[64:65], v[86:87], s[12:13] op_sel_hi:[1,0]
	v_pk_mul_f32 v[86:87], v[86:87], v[94:95]
	v_exp_f32_e32 v64, v64
	v_exp_f32_e32 v65, v65
	global_store_dwordx4 v216, v[166:169], s[42:43]
	v_pk_add_f32 v[64:65], v[64:65], 1.0 op_sel_hi:[1,0]
	v_rcp_f32_e32 v64, v64
	v_rcp_f32_e32 v65, v65
	s_nop 0
	v_pk_mul_f32 v[64:65], v[86:87], v[64:65]
	v_cvt_pk_bf16_f32 v166, v64, v65
	v_pk_mul_f32 v[64:65], v[90:91], s[12:13] op_sel_hi:[1,0]
	v_exp_f32_e32 v64, v64
	v_exp_f32_e32 v65, v65
	v_pk_mul_f32 v[86:87], v[90:91], v[138:139]
	v_pk_add_f32 v[64:65], v[64:65], 1.0 op_sel_hi:[1,0]
	v_rcp_f32_e32 v64, v64
	v_rcp_f32_e32 v65, v65
	s_nop 0
	v_pk_mul_f32 v[64:65], v[86:87], v[64:65]
	v_pk_mul_f32 v[86:87], v[76:77], s[12:13] op_sel_hi:[1,0]
;     static __device__ __forceinline__ unsigned silu_pk(const f32x2 g, const f32x2 v) {
;         const f32x2 t = g * -1.4426950408889634f;
;         const f32x2 d = (f32x2){__builtin_amdgcn_exp2f(t.x), __builtin_amdgcn_exp2f(t.y)} + 1.0f;
;         const f32x2 o = g * v * (f32x2){__builtin_amdgcn_rcpf(d.x), __builtin_amdgcn_rcpf(d.y)};
;         return cvt_pk_bf16(o.x, o.y);
;     }
;     __device__ __forceinline__ void operator()(f32x4 (&acc)[2][2][4][2], const Unit& u, int wr, int wc, int lane) const {
;         const int fr = lane & 15, fq = lane >> 4;
;         const int colu = u.pn * 128 + wc * 32;
;         const GAS float* cwu = cw + colu; const GAS float* cbu = cb + colu;
;         u32x2 keep[2][4];
;         f32x4 wgt[2][8];
; #pragma unroll
;         for (int n = 0; n < 2; ++n) { const unsigned co = (unsigned)(8 * fq + 4 * n) * 4u;
;             wgt[n][0] = gld<f32x4>(cwu, co); wgt[n][1] = gld<f32x4>(cwu + NUP, co); wgt[n][2] = gld<f32x4>(cwu + 2 * NUP, co); wgt[n][3] = gld<f32x4>(cbu, co);
;             wgt[n][4] = gld<f32x4>(cwu + DFF, co); wgt[n][5] = gld<f32x4>(cwu + NUP + DFF, co); wgt[n][6] = gld<f32x4>(cwu + 2 * NUP + DFF, co); wgt[n][7] = gld<f32x4>(cbu + DFF, co); }
; #pragma unroll
;         for (int n = 0; n < 2; ++n) {
;             const f32x4 wg0 = wgt[n][0], wg1 = wgt[n][1], wg2 = wgt[n][2], bg = wgt[n][3], wv0 = wgt[n][4], wv1 = wgt[n][5], wv2 = wgt[n][6], bvv = wgt[n][7];
; #pragma unroll
;             for (int ai = 0; ai < 2; ++ai) {
;                 const int blk = 4 * u.pm + 2 * ai + wr;
;                 GAS bf16_t* gu = G + (size_t)(u.pm * BM + ai * HALF + wr * 64) * DFF + colu;
;                 GAS bf16_t* eu = E + (size_t)blk * 4 * NUP + colu;
;                 f32x2 hg[4][2], hv[4][2];
;                 conv4(acc[ai][0][0][n], acc[ai][0][1][n], acc[ai][0][2][n], acc[ai][0][3][n], wg0, wg1, wg2, bg, hg);
;                 conv4(acc[ai][1][0][n], acc[ai][1][1][n], acc[ai][1][2][n], acc[ai][1][3][n], wv0, wv1, wv2, bvv, hv);
; #pragma unroll
;                 for (int m = 0; m < 4; ++m) {
;                     u32x2 w; w.x = silu_pk(hg[m][0], hv[m][0]); w.y = silu_pk(hg[m][1], hv[m][1]);
;                     if (n == 0) keep[ai][m] = w;
;                     else { u32x4 w4; w4.x = keep[ai][m].x; w4.y = keep[ai][m].y; w4.z = w.x; w4.w = w.y; gst<u32x4>(gu, ((unsigned)(4 * fr + m) * DFF + 8u * fq) * 2u, w4); }
	v_pk_mul_f32 v[76:77], v[76:77], v[84:85]
	v_exp_f32_e32 v86, v86
	v_exp_f32_e32 v87, v87
	v_cvt_pk_bf16_f32 v167, v64, v65
	v_add_u32_e32 v64, 0x1600, v216
	global_store_dwordx4 v64, v[164:167], s[42:43]
	v_pk_add_f32 v[86:87], v[86:87], 1.0 op_sel_hi:[1,0]
	v_mov_b32_e32 v65, v217
	v_rcp_f32_e32 v84, v86
	v_rcp_f32_e32 v85, v87
	s_nop 0
	v_pk_mul_f32 v[76:77], v[76:77], v[84:85]
	v_cvt_pk_bf16_f32 v164, v76, v77
	v_pk_mul_f32 v[76:77], v[68:69], s[12:13] op_sel_hi:[1,0]
	v_exp_f32_e32 v76, v76
	v_exp_f32_e32 v77, v77
	v_pk_mul_f32 v[68:69], v[68:69], v[78:79]
	v_pk_add_f32 v[76:77], v[76:77], 1.0 op_sel_hi:[1,0]
	v_rcp_f32_e32 v76, v76
	v_rcp_f32_e32 v77, v77
	s_nop 0
	v_pk_mul_f32 v[68:69], v[68:69], v[76:77]
	v_pk_mul_f32 v[76:77], v[70:71], s[12:13] op_sel_hi:[1,0]
	v_pk_mul_f32 v[70:71], v[70:71], v[74:75]
	v_exp_f32_e32 v76, v76
	v_exp_f32_e32 v77, v77
	v_cvt_pk_bf16_f32 v165, v68, v69
	v_mad_u32_u24 v68, v204, s92, v136
	global_store_dwordx4 v68, v[162:165], s[42:43]
	v_pk_add_f32 v[76:77], v[76:77], 1.0 op_sel_hi:[1,0]
	v_mov_b32_e32 v69, v217
	v_rcp_f32_e32 v74, v76
	v_rcp_f32_e32 v75, v77
	s_nop 0
	v_pk_mul_f32 v[70:71], v[70:71], v[74:75]
	v_cvt_pk_bf16_f32 v162, v70, v71
	v_pk_mul_f32 v[70:71], v[66:67], s[12:13] op_sel_hi:[1,0]
	v_exp_f32_e32 v70, v70
	v_exp_f32_e32 v71, v71
	v_pk_mul_f32 v[66:67], v[66:67], v[72:73]
	v_pk_add_f32 v[70:71], v[70:71], 1.0 op_sel_hi:[1,0]
	v_rcp_f32_e32 v70, v70
	v_rcp_f32_e32 v71, v71
	s_nop 0
	v_pk_mul_f32 v[66:67], v[66:67], v[70:71]
	v_cvt_pk_bf16_f32 v163, v66, v67
	v_add_u32_e32 v66, 0x4200, v216
	global_store_dwordx4 v66, v[160:163], s[42:43]
	v_mov_b32_e32 v67, v217
	v_cmp_gt_i32_e64 s[42:43], 15, v204
	s_and_saveexec_b64 s[52:53], s[42:43]
	v_cmp_eq_u32_e64 s[42:43], 0, v204
	s_orn2_b64 s[48:49], s[42:43], exec
	s_or_b64 exec, exec, s[52:53]
	v_or_b32_e32 v70, 8, v205
	v_mul_u32_u24_e32 v72, 0x2c00, v206
	s_movk_i32 s42, 0x2c08
	v_mad_u32_u24 v71, v206, s89, v70
	v_add3_u32 v70, v205, v72, s42
	s_and_saveexec_b64 s[42:43], s[48:49]
	s_cbranch_execz .LBB0_148
	s_add_u32 s48, s34, s62
	s_addc_u32 s49, s35, s61
	s_add_u32 s48, s48, s44
	s_addc_u32 s49, s49, s45
	s_add_u32 s52, s48, 0x1600
	v_cndmask_b32_e32 v58, v58, v62, vcc
	v_cndmask_b32_e32 v59, v59, v63, vcc
	v_cndmask_b32_e32 v56, v56, v60, vcc
	v_cndmask_b32_e32 v57, v57, v61, vcc
	v_cndmask_b32_e32 v44, v44, v36, vcc
	v_cndmask_b32_e32 v45, v45, v37, vcc
	v_cvt_pk_f16_f32 v36, v56, v57
	v_cvt_pk_f16_f32 v37, v58, v59
	s_addc_u32 s53, s49, 0
	v_cndmask_b32_e32 v38, v46, v38, vcc
	v_cndmask_b32_e32 v39, v47, v39, vcc
	global_store_dwordx2 v71, v[36:37], s[48:49]
	v_cvt_pk_f16_f32 v36, v44, v45
	v_cvt_pk_f16_f32 v37, v38, v39
	global_store_dwordx2 v71, v[36:37], s[52:53]
	v_cndmask_b32_e32 v36, v50, v54, vcc
	v_cndmask_b32_e32 v37, v51, v55, vcc
	v_cndmask_b32_e32 v38, v48, v52, vcc
	v_cndmask_b32_e32 v39, v49, v53, vcc
	v_cndmask_b32_e32 v40, v40, v32, vcc
	v_cndmask_b32_e32 v41, v41, v33, vcc
	v_cvt_pk_f16_f32 v32, v38, v39
	v_cvt_pk_f16_f32 v33, v36, v37
	v_cndmask_b32_e32 v34, v42, v34, vcc
	v_cndmask_b32_e32 v35, v43, v35, vcc
	global_store_dwordx2 v70, v[32:33], s[48:49]
	v_cvt_pk_f16_f32 v32, v40, v41
	v_cvt_pk_f16_f32 v33, v34, v35
	global_store_dwordx2 v70, v[32:33], s[52:53]
.LBB0_148:
	s_or_b64 exec, exec, s[42:43]
	v_mov_b32_dpp v32, v8 row_shr:1 row_mask:0xf bank_mask:0xf bound_ctrl:1
	v_mov_b32_dpp v33, v9 row_shr:1 row_mask:0xf bank_mask:0xf bound_ctrl:1
	v_mov_b32_dpp v34, v4 row_shl:1 row_mask:0xf bank_mask:0xf bound_ctrl:1
	v_mov_b32_dpp v35, v5 row_shl:1 row_mask:0xf bank_mask:0xf bound_ctrl:1
	s_add_i32 s42, s56, 0x80
	v_pk_fma_f32 v[32:33], v[80:81], v[32:33], v[108:109]
	s_mul_hi_i32 s43, s42, 0x1600
	v_pk_fma_f32 v[32:33], v[4:5], v[96:97], v[32:33]
	s_mulk_i32 s42, 0x1600
	v_pk_fma_f32 v[48:49], v[0:1], v[104:105], v[32:33]
	v_pk_fma_f32 v[32:33], v[4:5], v[80:81], v[108:109]
	s_add_u32 s42, s31, s42
	v_pk_fma_f32 v[32:33], v[0:1], v[96:97], v[32:33]
	s_addc_u32 s43, s33, s43
	v_pk_fma_f32 v[50:51], v[16:17], v[104:105], v[32:33]
	v_pk_fma_f32 v[32:33], v[0:1], v[80:81], v[108:109]
	s_add_u32 s42, s42, s44
	v_pk_fma_f32 v[32:33], v[16:17], v[96:97], v[32:33]
	s_addc_u32 s43, s43, s45
	v_pk_fma_f32 v[42:43], v[8:9], v[104:105], v[32:33]
	v_pk_fma_f32 v[32:33], v[16:17], v[80:81], v[108:109]
	s_mov_b64 s[48:49], -1
	v_pk_fma_f32 v[32:33], v[8:9], v[96:97], v[32:33]
	v_pk_fma_f32 v[34:35], v[104:105], v[34:35], v[32:33]
	v_mov_b32_dpp v32, v10 row_shr:1 row_mask:0xf bank_mask:0xf bound_ctrl:1
	v_mov_b32_dpp v33, v11 row_shr:1 row_mask:0xf bank_mask:0xf bound_ctrl:1
	v_mov_b32_dpp v36, v6 row_shl:1 row_mask:0xf bank_mask:0xf bound_ctrl:1
	v_mov_b32_dpp v37, v7 row_shl:1 row_mask:0xf bank_mask:0xf bound_ctrl:1
	v_pk_fma_f32 v[32:33], v[82:83], v[32:33], v[110:111]
	v_pk_fma_f32 v[32:33], v[6:7], v[98:99], v[32:33]
	v_pk_fma_f32 v[52:53], v[2:3], v[106:107], v[32:33]
	v_pk_fma_f32 v[32:33], v[6:7], v[82:83], v[110:111]
	v_pk_fma_f32 v[32:33], v[2:3], v[98:99], v[32:33]
	v_pk_fma_f32 v[54:55], v[18:19], v[106:107], v[32:33]
	v_pk_fma_f32 v[32:33], v[2:3], v[82:83], v[110:111]
	v_pk_fma_f32 v[32:33], v[18:19], v[98:99], v[32:33]
	v_pk_fma_f32 v[40:41], v[10:11], v[106:107], v[32:33]
	v_pk_fma_f32 v[32:33], v[18:19], v[82:83], v[110:111]
	v_pk_fma_f32 v[32:33], v[10:11], v[98:99], v[32:33]
; #define GAS __attribute__((address_space(1)))
;     __device__ __forceinline__ void conv4(const f32x4& a0, const f32x4& a1, const f32x4& a2, const f32x4& a3, const f32x4& w0, const f32x4& w1, const f32x4& w2, const f32x4& b, f32x2 (&h)[4][2]) const {
; #pragma unroll
;         for (int p = 0; p < 2; ++p) {
;             float u0, u1, d0, d1;
;             asm volatile("s_nop 1\n\tv_mov_b32_dpp %0, %1 row_shr:1 row_mask:0xf bank_mask:0xf bound_ctrl:1" : "=&v"(u0) : "v"(a3[2 * p]));
;             asm volatile("s_nop 1\n\tv_mov_b32_dpp %0, %1 row_shr:1 row_mask:0xf bank_mask:0xf bound_ctrl:1" : "=&v"(u1) : "v"(a3[2 * p + 1]));
;             asm volatile("s_nop 1\n\tv_mov_b32_dpp %0, %1 row_shl:1 row_mask:0xf bank_mask:0xf bound_ctrl:1" : "=&v"(d0) : "v"(a0[2 * p]));
;             asm volatile("s_nop 1\n\tv_mov_b32_dpp %0, %1 row_shl:1 row_mask:0xf bank_mask:0xf bound_ctrl:1" : "=&v"(d1) : "v"(a0[2 * p + 1]));
;             const f32x2 UP = {u0, u1}, DN = {d0, d1};
;             const f32x2 A0 = {a0[2 * p], a0[2 * p + 1]}, A1 = {a1[2 * p], a1[2 * p + 1]}, A2 = {a2[2 * p], a2[2 * p + 1]}, A3 = {a3[2 * p], a3[2 * p + 1]};
;             const f32x2 W0 = {w0[2 * p], w0[2 * p + 1]}, W1 = {w1[2 * p], w1[2 * p + 1]}, W2 = {w2[2 * p], w2[2 * p + 1]}, B = {b[2 * p], b[2 * p + 1]};
;             h[0][p] = B + W0 * UP + W1 * A0 + W2 * A1;
;             h[1][p] = B + W0 * A0 + W1 * A1 + W2 * A2;
;             h[2][p] = B + W0 * A1 + W1 * A2 + W2 * A3;
;             h[3][p] = B + W0 * A2 + W1 * A3 + W2 * DN;
;         }
;     }
;     static __device__ __forceinline__ unsigned silu_pk(const f32x2 g, const f32x2 v) {
;         const f32x2 t = g * -1.4426950408889634f;
;         const f32x2 d = (f32x2){__builtin_amdgcn_exp2f(t.x), __builtin_amdgcn_exp2f(t.y)} + 1.0f;
;         const f32x2 o = g * v * (f32x2){__builtin_amdgcn_rcpf(d.x), __builtin_amdgcn_rcpf(d.y)};
;         return cvt_pk_bf16(o.x, o.y);
;     }
;     __device__ __forceinline__ void operator()(f32x4 (&acc)[2][2][4][2], const Unit& u, int wr, int wc, int lane) const {
;         const int fr = lane & 15, fq = lane >> 4;
;         const int colu = u.pn * 128 + wc * 32;
;         const GAS float* cwu = cw + colu; const GAS float* cbu = cb + colu;
;         u32x2 keep[2][4];
;         f32x4 wgt[2][8];
; #pragma unroll
;         for (int n = 0; n < 2; ++n) { const unsigned co = (unsigned)(8 * fq + 4 * n) * 4u;
	v_pk_fma_f32 v[32:33], v[106:107], v[36:37], v[32:33]
	v_mov_b32_dpp v36, v24 row_shr:1 row_mask:0xf bank_mask:0xf bound_ctrl:1
	v_mov_b32_dpp v37, v25 row_shr:1 row_mask:0xf bank_mask:0xf bound_ctrl:1
	v_mov_b32_dpp v38, v20 row_shl:1 row_mask:0xf bank_mask:0xf bound_ctrl:1
	v_mov_b32_dpp v39, v21 row_shl:1 row_mask:0xf bank_mask:0xf bound_ctrl:1
	v_pk_fma_f32 v[36:37], v[112:113], v[36:37], v[124:125]
	v_pk_fma_f32 v[36:37], v[20:21], v[116:117], v[36:37]
	v_pk_fma_f32 v[56:57], v[12:13], v[120:121], v[36:37]
	v_pk_fma_f32 v[36:37], v[20:21], v[112:113], v[124:125]
	v_pk_fma_f32 v[36:37], v[12:13], v[116:117], v[36:37]
	v_pk_fma_f32 v[58:59], v[28:29], v[120:121], v[36:37]
	v_pk_fma_f32 v[36:37], v[12:13], v[112:113], v[124:125]
	v_pk_fma_f32 v[36:37], v[28:29], v[116:117], v[36:37]
	v_pk_fma_f32 v[46:47], v[24:25], v[120:121], v[36:37]
	v_pk_fma_f32 v[36:37], v[28:29], v[112:113], v[124:125]
	v_pk_fma_f32 v[36:37], v[24:25], v[116:117], v[36:37]
	v_pk_fma_f32 v[38:39], v[120:121], v[38:39], v[36:37]
	v_mov_b32_dpp v36, v26 row_shr:1 row_mask:0xf bank_mask:0xf bound_ctrl:1
	v_mov_b32_dpp v37, v27 row_shr:1 row_mask:0xf bank_mask:0xf bound_ctrl:1
	v_mov_b32_dpp v60, v22 row_shl:1 row_mask:0xf bank_mask:0xf bound_ctrl:1
	v_mov_b32_dpp v61, v23 row_shl:1 row_mask:0xf bank_mask:0xf bound_ctrl:1
	v_pk_fma_f32 v[36:37], v[114:115], v[36:37], v[126:127]
	v_pk_fma_f32 v[36:37], v[22:23], v[118:119], v[36:37]
	v_pk_fma_f32 v[62:63], v[14:15], v[122:123], v[36:37]
	v_pk_fma_f32 v[36:37], v[22:23], v[114:115], v[126:127]
	v_pk_fma_f32 v[36:37], v[14:15], v[118:119], v[36:37]
	v_pk_fma_f32 v[72:73], v[30:31], v[122:123], v[36:37]
	v_pk_fma_f32 v[36:37], v[14:15], v[114:115], v[126:127]
	v_pk_fma_f32 v[36:37], v[30:31], v[118:119], v[36:37]
	v_pk_fma_f32 v[44:45], v[26:27], v[122:123], v[36:37]
	v_pk_fma_f32 v[36:37], v[30:31], v[114:115], v[126:127]
	v_pk_fma_f32 v[36:37], v[26:27], v[118:119], v[36:37]
	v_pk_fma_f32 v[36:37], v[122:123], v[60:61], v[36:37]
	v_pk_mul_f32 v[60:61], v[48:49], s[12:13] op_sel_hi:[1,0]
	v_exp_f32_e32 v60, v60
	v_exp_f32_e32 v61, v61
	v_pk_mul_f32 v[48:49], v[48:49], v[56:57]
	v_pk_add_f32 v[60:61], v[60:61], 1.0 op_sel_hi:[1,0]
	v_rcp_f32_e32 v56, v60
	v_rcp_f32_e32 v57, v61
	s_nop 0
	v_pk_mul_f32 v[48:49], v[48:49], v[56:57]
	v_cvt_pk_bf16_f32 v136, v48, v49
	v_pk_mul_f32 v[48:49], v[52:53], s[12:13] op_sel_hi:[1,0]
	v_exp_f32_e32 v48, v48
	v_exp_f32_e32 v49, v49
	v_pk_mul_f32 v[52:53], v[52:53], v[62:63]
	v_pk_add_f32 v[48:49], v[48:49], 1.0 op_sel_hi:[1,0]
	v_rcp_f32_e32 v48, v48
	v_rcp_f32_e32 v49, v49
	s_nop 0
	v_pk_mul_f32 v[48:49], v[52:53], v[48:49]
	v_cvt_pk_bf16_f32 v137, v48, v49
	v_lshl_add_u64 v[48:49], s[42:43], 0, v[216:217]
	global_store_dwordx4 v[48:49], v[134:137], off
	v_pk_mul_f32 v[48:49], v[50:51], s[12:13] op_sel_hi:[1,0]
	v_exp_f32_e32 v48, v48
	v_exp_f32_e32 v49, v49
	v_pk_mul_f32 v[50:51], v[50:51], v[58:59]
	v_pk_add_f32 v[48:49], v[48:49], 1.0 op_sel_hi:[1,0]
	v_rcp_f32_e32 v48, v48
	v_rcp_f32_e32 v49, v49
	s_nop 0
	v_pk_mul_f32 v[48:49], v[50:51], v[48:49]
	v_cvt_pk_bf16_f32 v134, v48, v49
	v_pk_mul_f32 v[48:49], v[54:55], s[12:13] op_sel_hi:[1,0]
	v_exp_f32_e32 v48, v48
	v_exp_f32_e32 v49, v49
	v_pk_mul_f32 v[50:51], v[54:55], v[72:73]
	v_pk_add_f32 v[48:49], v[48:49], 1.0 op_sel_hi:[1,0]
	v_rcp_f32_e32 v48, v48
	v_rcp_f32_e32 v49, v49
	s_nop 0
	v_pk_mul_f32 v[48:49], v[50:51], v[48:49]
	v_cvt_pk_bf16_f32 v135, v48, v49
	v_lshl_add_u64 v[48:49], s[42:43], 0, v[64:65]
	global_store_dwordx4 v[48:49], v[132:135], off
	v_pk_mul_f32 v[48:49], v[42:43], s[12:13] op_sel_hi:[1,0]
	v_exp_f32_e32 v48, v48
	v_exp_f32_e32 v49, v49
	v_pk_mul_f32 v[42:43], v[42:43], v[46:47]
	v_pk_add_f32 v[48:49], v[48:49], 1.0 op_sel_hi:[1,0]
	v_rcp_f32_e32 v46, v48
	v_rcp_f32_e32 v47, v49
	s_nop 0
	v_pk_mul_f32 v[42:43], v[42:43], v[46:47]
	v_cvt_pk_bf16_f32 v132, v42, v43
	v_pk_mul_f32 v[42:43], v[40:41], s[12:13] op_sel_hi:[1,0]
	v_exp_f32_e32 v42, v42
	v_exp_f32_e32 v43, v43
	v_pk_mul_f32 v[40:41], v[40:41], v[44:45]
	v_pk_add_f32 v[42:43], v[42:43], 1.0 op_sel_hi:[1,0]
	v_rcp_f32_e32 v42, v42
	v_rcp_f32_e32 v43, v43
	s_nop 0
	v_pk_mul_f32 v[40:41], v[40:41], v[42:43]
	v_cvt_pk_bf16_f32 v133, v40, v41
	v_lshl_add_u64 v[40:41], s[42:43], 0, v[68:69]
	global_store_dwordx4 v[40:41], v[130:133], off
	v_pk_mul_f32 v[40:41], v[34:35], s[12:13] op_sel_hi:[1,0]
	v_exp_f32_e32 v40, v40
	v_exp_f32_e32 v41, v41
	v_pk_mul_f32 v[34:35], v[34:35], v[38:39]
	v_pk_add_f32 v[40:41], v[40:41], 1.0 op_sel_hi:[1,0]
	v_rcp_f32_e32 v38, v40
	v_rcp_f32_e32 v39, v41
	s_nop 0
	v_pk_mul_f32 v[34:35], v[34:35], v[38:39]
	v_cvt_pk_bf16_f32 v130, v34, v35
	v_pk_mul_f32 v[34:35], v[32:33], s[12:13] op_sel_hi:[1,0]
	v_exp_f32_e32 v34, v34
	v_exp_f32_e32 v35, v35
	v_pk_mul_f32 v[32:33], v[32:33], v[36:37]
	v_pk_add_f32 v[34:35], v[34:35], 1.0 op_sel_hi:[1,0]
	v_rcp_f32_e32 v34, v34
	v_rcp_f32_e32 v35, v35
	s_nop 0
	v_pk_mul_f32 v[32:33], v[32:33], v[34:35]
	v_cvt_pk_bf16_f32 v131, v32, v33
	v_lshl_add_u64 v[32:33], s[42:43], 0, v[66:67]
	v_cmp_gt_i32_e64 s[42:43], 15, v204
	global_store_dwordx4 v[32:33], v[128:131], off
	s_and_saveexec_b64 s[52:53], s[42:43]
	s_cbranch_execz .LBB0_151
	v_cmp_eq_u32_e64 s[42:43], 0, v204
	s_orn2_b64 s[48:49], s[42:43], exec
	s_or_b64 exec, exec, s[52:53]
	s_and_saveexec_b64 s[42:43], s[48:49]
	s_cbranch_execnz .LBB0_152

.LBB0_970:
	v_add_u32_e32 v65, s31, v189
	ds_read_b64_tr_b16 v[178:179], v65 offset:24576
	ds_read_b64_tr_b16 v[180:181], v65 offset:25088
	v_add_f32_e32 v86, v66, v67
	v_add_f32_e32 v86, v68, v86
	v_add_f32_e32 v86, v69, v86
	v_add_f32_e32 v86, v70, v86
	v_add_f32_e32 v86, v71, v86
	v_cvt_pk_bf16_f32 v142, v66, v67
	v_cvt_pk_bf16_f32 v143, v68, v69
	v_mfma_f32_32x32x16_bf16 v[98:113], v[82:85], v[158:161], v[32:47]
	ds_read_b64_tr_b16 v[174:175], v65 offset:28672
	ds_read_b64_tr_b16 v[176:177], v65 offset:29184
	v_add_f32_e32 v66, v72, v86
	v_mfma_f32_32x32x16_bf16 v[82:97], v[166:169], v[158:161], v[32:47]
	v_add_f32_e32 v66, v73, v66
	v_add_f32_e32 v66, v74, v66
	v_add_f32_e32 v130, v75, v66
	v_cvt_pk_bf16_f32 v144, v70, v71
	v_cvt_pk_bf16_f32 v145, v72, v73
	ds_read_b64_tr_b16 v[66:67], v65 offset:25600
	ds_read_b64_tr_b16 v[68:69], v65 offset:26112
	v_add_f32_e32 v70, v76, v130
	v_add_f32_e32 v70, v77, v70
	v_add_f32_e32 v70, v78, v70
	v_add_f32_e32 v130, v79, v70
	v_cvt_pk_bf16_f32 v138, v74, v75
	v_cvt_pk_bf16_f32 v139, v76, v77
	v_mfma_f32_32x32x16_bf16 v[98:113], v[170:173], v[154:157], v[98:113]
	ds_read_b64_tr_b16 v[70:71], v65 offset:29696
	ds_read_b64_tr_b16 v[72:73], v65 offset:30208
	v_mfma_f32_32x32x16_bf16 v[82:97], v[162:165], v[154:157], v[82:97]
	v_add_f32_e32 v74, v80, v130
	v_add_f32_e32 v74, v81, v74
	v_add_f32_e32 v74, v48, v74
	v_add_f32_e32 v130, v49, v74
	v_cvt_pk_bf16_f32 v140, v78, v79
	v_cvt_pk_bf16_f32 v141, v80, v81
	ds_read_b64_tr_b16 v[74:75], v65 offset:26624
	ds_read_b64_tr_b16 v[76:77], v65 offset:27136
	v_add_f32_e32 v78, v50, v130
	v_add_f32_e32 v78, v51, v78
	v_add_f32_e32 v78, v52, v78
	v_add_f32_e32 v78, v53, v78
	v_cvt_pk_bf16_f32 v134, v48, v49
	v_cvt_pk_bf16_f32 v135, v50, v51
	v_mfma_f32_32x32x16_bf16 v[98:113], v[126:129], v[150:153], v[98:113]
	ds_read_b64_tr_b16 v[48:49], v65 offset:30720
	ds_read_b64_tr_b16 v[50:51], v65 offset:31232
	v_mfma_f32_32x32x16_bf16 v[82:97], v[122:125], v[150:153], v[82:97]
	v_add_f32_e32 v78, v54, v78
	v_add_f32_e32 v78, v55, v78
	v_add_f32_e32 v78, v56, v78
	v_add_f32_e32 v78, v57, v78
	v_cvt_pk_bf16_f32 v136, v52, v53
	v_cvt_pk_bf16_f32 v137, v54, v55
	ds_read_b64_tr_b16 v[52:53], v65 offset:27648
	ds_read_b64_tr_b16 v[54:55], v65 offset:28160
	v_add_f32_e32 v78, v58, v78
	v_add_f32_e32 v78, v59, v78
	v_add_f32_e32 v78, v60, v78
	v_add_f32_e32 v78, v61, v78
	v_cvt_pk_bf16_f32 v130, v56, v57
	v_cvt_pk_bf16_f32 v131, v58, v59
	v_mfma_f32_32x32x16_bf16 v[98:113], v[118:121], v[146:149], v[98:113]
	ds_read_b64_tr_b16 v[56:57], v65 offset:31744
	ds_read_b64_tr_b16 v[58:59], v65 offset:32256
	v_mfma_f32_32x32x16_bf16 v[82:97], v[114:117], v[146:149], v[82:97]
	v_add_f32_e32 v65, v62, v78
	v_add_f32_e32 v65, v63, v65
	v_cvt_pk_bf16_f32 v132, v60, v61
	v_cvt_pk_bf16_f32 v133, v62, v63
	v_add_f32_e32 v64, v64, v65
	s_waitcnt lgkmcnt(12)
	v_mfma_f32_32x32x16_bf16 v[0:15], v[142:145], v[178:181], v[0:15]
	s_add_u32 s31, s16, s22
	s_addc_u32 s33, s17, 0
	s_add_i32 m0, s29, s18
	s_add_u32 s34, s31, 0x9ac0800
	s_addc_u32 s35, s33, 0
	global_load_lds_dwordx4 v184, s[34:35]
	v_exp_f32_e32 v98, v98
	v_exp_f32_e32 v99, v99
	v_exp_f32_e32 v100, v100
	v_exp_f32_e32 v101, v101
	v_mfma_f32_32x32x16_bf16 v[16:31], v[142:145], v[174:177], v[16:31]
	s_add_u32 s34, s20, s22
	s_addc_u32 s35, s21, 0
	s_add_i32 m0, s28, s15
	s_add_u32 s36, s34, 0x9a60a00
	s_addc_u32 s37, s35, 0
	global_load_lds_dwordx4 v185, s[36:37]
	v_exp_f32_e32 v102, v102
	v_exp_f32_e32 v103, v103
	v_exp_f32_e32 v104, v104
	v_exp_f32_e32 v105, v105
	s_waitcnt lgkmcnt(0)
	v_add_u32_e32 v65, s28, v187
	ds_read_b128 v[60:63], v65
	ds_read_b128 v[118:121], v65 offset:512
	v_mfma_f32_32x32x16_bf16 v[0:15], v[138:141], v[66:69], v[0:15]
	v_exp_f32_e32 v106, v106
	v_exp_f32_e32 v107, v107
	v_exp_f32_e32 v108, v108
	v_exp_f32_e32 v109, v109
	ds_read_b128 v[122:125], v65 offset:2048
	ds_read_b128 v[126:129], v65 offset:2560
	v_mfma_f32_32x32x16_bf16 v[16:31], v[138:141], v[70:73], v[16:31]
	v_exp_f32_e32 v110, v110
	v_exp_f32_e32 v111, v111
	v_exp_f32_e32 v112, v112
	v_exp_f32_e32 v113, v113
	ds_read_b128 v[162:165], v65 offset:4096
	ds_read_b128 v[166:169], v65 offset:4608
	v_mfma_f32_32x32x16_bf16 v[0:15], v[134:137], v[74:77], v[0:15]
	v_exp_f32_e32 v82, v82
	v_exp_f32_e32 v83, v83
	v_exp_f32_e32 v84, v84
	v_exp_f32_e32 v85, v85
	ds_read_b128 v[170:173], v65 offset:6144
	ds_read_b128 v[114:117], v65 offset:6656
	v_mfma_f32_32x32x16_bf16 v[16:31], v[134:137], v[48:51], v[16:31]
	v_exp_f32_e32 v86, v86
	v_exp_f32_e32 v87, v87
	v_exp_f32_e32 v88, v88
	v_exp_f32_e32 v89, v89
	v_mfma_f32_32x32x16_bf16 v[0:15], v[130:133], v[52:55], v[0:15]
	v_exp_f32_e32 v90, v90
	v_exp_f32_e32 v91, v91
	v_exp_f32_e32 v92, v92
	v_exp_f32_e32 v93, v93
	v_mfma_f32_32x32x16_bf16 v[16:31], v[130:133], v[56:59], v[16:31]
	v_exp_f32_e32 v94, v94
	v_exp_f32_e32 v95, v95
	v_exp_f32_e32 v96, v96
	v_exp_f32_e32 v97, v97
	s_waitcnt vmcnt(2) lgkmcnt(0)
	s_barrier
; #define WAIT_BAR(N) asm volatile("s_waitcnt vmcnt(" #N ") lgkmcnt(0)\n\ts_barrier" ::: "memory")
;   #define RESC() do { if constexpr (!NOMAX) if (resc) { asm volatile("s_waitcnt lgkmcnt(0)" ::: "memory"); \
;       _Pragma("unroll") for (int d_ = 0; d_ < 2 * DV2; ++d_) _Pragma("unroll") for (int r = 0; r < 16; ++r) o[d_][r] *= wsf[crow(r, hi)]; } } while (0)
;   #define ROT() do { sl_prev = sl_cur; sl_cur = sl_next; sl_next = (sl_next == (NSLOT - 1) * SLOTB) ? 0 : sl_next + SLOTB; } while (0)
;     ...
;   int t = 1;
;   for (; t + 5 < NT; t += 2) {
;     STEP(pB0, pB1, pA0, pA1, t, true, true, true);     if constexpr (DV2 == 2) { WAIT_BAR(3); } else { WAIT_BAR(2); } RESC(); ROT();
;     STEP(pA0, pA1, pB0, pB1, t + 1, true, true, true); if constexpr (DV2 == 2) { WAIT_BAR(3); } else { WAIT_BAR(2); } RESC(); ROT();
	s_add_i32 s30, s28, 0x2000
	s_cmpk_lg_i32 s28, 0x4000
	s_cselect_b32 s30, s30, 0
	v_add_u32_e32 v65, s29, v189
	ds_read_b64_tr_b16 v[174:175], v65 offset:24576
	ds_read_b64_tr_b16 v[176:177], v65 offset:25088
	v_mfma_f32_32x32x16_bf16 v[66:81], v[60:63], v[158:161], v[32:47]
	v_add_f32_e32 v48, v98, v99
	v_add_f32_e32 v48, v100, v48
	v_add_f32_e32 v48, v101, v48
	v_add_f32_e32 v48, v102, v48
	v_add_f32_e32 v48, v103, v48
	v_cvt_pk_bf16_f32 v142, v98, v99
	v_cvt_pk_bf16_f32 v143, v100, v101
	ds_read_b64_tr_b16 v[178:179], v65 offset:28672
	ds_read_b64_tr_b16 v[180:181], v65 offset:29184
	v_add_f32_e32 v48, v104, v48
	v_add_f32_e32 v48, v105, v48
	v_add_f32_e32 v48, v106, v48
	v_add_f32_e32 v130, v107, v48
	v_mfma_f32_32x32x16_bf16 v[48:63], v[118:121], v[158:161], v[32:47]
	v_cvt_pk_bf16_f32 v144, v102, v103
	v_cvt_pk_bf16_f32 v145, v104, v105
	ds_read_b64_tr_b16 v[98:99], v65 offset:25600
	ds_read_b64_tr_b16 v[100:101], v65 offset:26112
	v_mfma_f32_32x32x16_bf16 v[66:81], v[122:125], v[154:157], v[66:81]
	v_add_f32_e32 v102, v108, v130
	v_add_f32_e32 v102, v109, v102
	v_add_f32_e32 v102, v110, v102
	v_add_f32_e32 v118, v111, v102
	v_cvt_pk_bf16_f32 v138, v106, v107
	v_cvt_pk_bf16_f32 v139, v108, v109
	ds_read_b64_tr_b16 v[102:103], v65 offset:29696
	ds_read_b64_tr_b16 v[104:105], v65 offset:30208
	v_mfma_f32_32x32x16_bf16 v[48:63], v[126:129], v[154:157], v[48:63]
	v_add_f32_e32 v106, v112, v118
	v_add_f32_e32 v106, v113, v106
	v_add_f32_e32 v106, v82, v106
	v_add_f32_e32 v118, v83, v106
	v_cvt_pk_bf16_f32 v140, v110, v111
	v_cvt_pk_bf16_f32 v141, v112, v113
	ds_read_b64_tr_b16 v[106:107], v65 offset:26624
	ds_read_b64_tr_b16 v[108:109], v65 offset:27136
	v_mfma_f32_32x32x16_bf16 v[66:81], v[162:165], v[150:153], v[66:81]
	v_add_f32_e32 v110, v84, v118
	v_add_f32_e32 v110, v85, v110
	v_add_f32_e32 v110, v86, v110
	v_add_f32_e32 v118, v87, v110
	v_cvt_pk_bf16_f32 v134, v82, v83
	v_cvt_pk_bf16_f32 v135, v84, v85
	ds_read_b64_tr_b16 v[110:111], v65 offset:30720
	ds_read_b64_tr_b16 v[112:113], v65 offset:31232
	v_mfma_f32_32x32x16_bf16 v[48:63], v[166:169], v[150:153], v[48:63]
	v_add_f32_e32 v82, v88, v118
	v_add_f32_e32 v82, v89, v82
	v_add_f32_e32 v82, v90, v82
	v_add_f32_e32 v82, v91, v82
	v_cvt_pk_bf16_f32 v136, v86, v87
	v_cvt_pk_bf16_f32 v137, v88, v89
	ds_read_b64_tr_b16 v[86:87], v65 offset:27648
	ds_read_b64_tr_b16 v[88:89], v65 offset:28160
	v_mfma_f32_32x32x16_bf16 v[66:81], v[170:173], v[146:149], v[66:81]
	v_add_f32_e32 v82, v92, v82
	v_add_f32_e32 v82, v93, v82
	v_add_f32_e32 v82, v94, v82
	v_add_f32_e32 v82, v95, v82
	v_cvt_pk_bf16_f32 v130, v90, v91
	v_cvt_pk_bf16_f32 v131, v92, v93
	ds_read_b64_tr_b16 v[90:91], v65 offset:31744
	ds_read_b64_tr_b16 v[92:93], v65 offset:32256
	v_mfma_f32_32x32x16_bf16 v[48:63], v[114:117], v[146:149], v[48:63]
	v_add_f32_e32 v65, v96, v82
	v_add_f32_e32 v65, v97, v65
	v_cvt_pk_bf16_f32 v132, v94, v95
	v_cvt_pk_bf16_f32 v133, v96, v97
	v_add_f32_e32 v64, v64, v65
	s_waitcnt lgkmcnt(12)
	v_mfma_f32_32x32x16_bf16 v[0:15], v[142:145], v[174:177], v[0:15]
	s_add_i32 m0, s28, s18
	s_add_u32 s36, s31, 0x9af0800
	s_addc_u32 s37, s33, 0
	global_load_lds_dwordx4 v184, s[36:37]
	v_exp_f32_e32 v66, v66
	v_exp_f32_e32 v67, v67
	v_exp_f32_e32 v68, v68
	v_exp_f32_e32 v69, v69
	v_mfma_f32_32x32x16_bf16 v[16:31], v[142:145], v[178:181], v[16:31]
	s_add_i32 m0, s30, s15
	s_add_u32 s34, s34, 0x9a90a00
	s_addc_u32 s35, s35, 0
	global_load_lds_dwordx4 v185, s[34:35]
	v_exp_f32_e32 v70, v70
	v_exp_f32_e32 v71, v71
	v_exp_f32_e32 v72, v72
	v_exp_f32_e32 v73, v73
	v_add_u32_e32 v65, s30, v187
	ds_read_b128 v[82:85], v65
	ds_read_b128 v[166:169], v65 offset:512
	v_mfma_f32_32x32x16_bf16 v[0:15], v[138:141], v[98:101], v[0:15]
	v_exp_f32_e32 v74, v74
	s_waitcnt lgkmcnt(0)
	v_exp_f32_e32 v75, v75
	v_exp_f32_e32 v76, v76
	v_exp_f32_e32 v77, v77
	ds_read_b128 v[170:173], v65 offset:2048
	ds_read_b128 v[162:165], v65 offset:2560
	v_mfma_f32_32x32x16_bf16 v[16:31], v[138:141], v[102:105], v[16:31]
	v_exp_f32_e32 v78, v78
	v_exp_f32_e32 v79, v79
	v_exp_f32_e32 v80, v80
	v_exp_f32_e32 v81, v81
	ds_read_b128 v[126:129], v65 offset:4096
	ds_read_b128 v[122:125], v65 offset:4608
	v_mfma_f32_32x32x16_bf16 v[0:15], v[134:137], v[106:109], v[0:15]
	v_exp_f32_e32 v48, v48
	v_exp_f32_e32 v49, v49
	v_exp_f32_e32 v50, v50
	v_exp_f32_e32 v51, v51
	ds_read_b128 v[118:121], v65 offset:6144
	ds_read_b128 v[114:117], v65 offset:6656
	v_mfma_f32_32x32x16_bf16 v[16:31], v[134:137], v[110:113], v[16:31]
	v_exp_f32_e32 v52, v52
	v_exp_f32_e32 v53, v53
	v_exp_f32_e32 v54, v54
	v_exp_f32_e32 v55, v55
	v_mfma_f32_32x32x16_bf16 v[0:15], v[130:133], v[86:89], v[0:15]
	v_exp_f32_e32 v56, v56
	v_exp_f32_e32 v57, v57
	v_exp_f32_e32 v58, v58
	v_exp_f32_e32 v59, v59
	v_mfma_f32_32x32x16_bf16 v[16:31], v[130:133], v[90:93], v[16:31]
	v_exp_f32_e32 v60, v60
	v_exp_f32_e32 v61, v61
	v_exp_f32_e32 v62, v62
	v_exp_f32_e32 v63, v63
	s_add_i32 s33, s30, 0x2000
	s_cmpk_lg_i32 s30, 0x4000
	s_mov_b32 s31, s28
	s_cselect_b32 s28, s33, 0
	s_add_i32 s24, s24, 2
	s_add_u32 s20, s20, 0x60000
	s_addc_u32 s21, s21, 0
	s_waitcnt vmcnt(2) lgkmcnt(0)
	s_barrier
	s_add_u32 s16, s16, 0x60000
	s_addc_u32 s17, s17, 0
	s_mov_b32 s29, s30
	s_cmp_gt_u32 s24, 56
	s_cbranch_scc0 .LBB0_970
	s_and_b32 s16, s23, 0x3fffffc0
	s_lshl_b32 s16, s16, 2
	s_add_i32 s16, s16, 0
	ds_read_b64_tr_b16 v[174:175], v189 offset:32768
	ds_read_b64_tr_b16 v[176:177], v189 offset:33280
	v_add_f32_e32 v65, v66, v67
	v_add_f32_e32 v65, v68, v65
	v_add_f32_e32 v65, v69, v65
	v_add_f32_e32 v65, v70, v65
	v_add_f32_e32 v65, v71, v65
	v_cvt_pk_bf16_f32 v142, v66, v67
	v_cvt_pk_bf16_f32 v143, v68, v69
	s_waitcnt lgkmcnt(9)
	v_mfma_f32_32x32x16_bf16 v[98:113], v[82:85], v[158:161], v[32:47]
	ds_read_b64_tr_b16 v[178:179], v189 offset:36864
	ds_read_b64_tr_b16 v[180:181], v189 offset:37376
	v_add_f32_e32 v65, v72, v65
	v_add_f32_e32 v65, v73, v65
	v_add_f32_e32 v65, v74, v65
	v_add_f32_e32 v65, v75, v65
	v_cvt_pk_bf16_f32 v144, v70, v71
	v_cvt_pk_bf16_f32 v145, v72, v73
	s_waitcnt lgkmcnt(10)
	v_mfma_f32_32x32x16_bf16 v[82:97], v[166:169], v[158:161], v[32:47]
	ds_read_b64_tr_b16 v[66:67], v189 offset:33792
	ds_read_b64_tr_b16 v[68:69], v189 offset:34304
	v_add_f32_e32 v65, v76, v65
	v_add_f32_e32 v65, v77, v65
	v_add_f32_e32 v65, v78, v65
	v_add_f32_e32 v65, v79, v65
	v_cvt_pk_bf16_f32 v138, v74, v75
	v_cvt_pk_bf16_f32 v139, v76, v77
	s_waitcnt lgkmcnt(11)
	v_mfma_f32_32x32x16_bf16 v[98:113], v[170:173], v[154:157], v[98:113]
	ds_read_b64_tr_b16 v[70:71], v189 offset:37888
	ds_read_b64_tr_b16 v[72:73], v189 offset:38400
	v_add_f32_e32 v65, v80, v65
	v_add_f32_e32 v65, v81, v65
	v_add_f32_e32 v65, v48, v65
	v_add_f32_e32 v65, v49, v65
	v_cvt_pk_bf16_f32 v140, v78, v79
	v_cvt_pk_bf16_f32 v141, v80, v81
	s_waitcnt lgkmcnt(12)
	v_mfma_f32_32x32x16_bf16 v[82:97], v[162:165], v[154:157], v[82:97]
	ds_read_b64_tr_b16 v[74:75], v189 offset:34816
	ds_read_b64_tr_b16 v[76:77], v189 offset:35328
	v_add_f32_e32 v65, v50, v65
	v_add_f32_e32 v65, v51, v65
	v_add_f32_e32 v65, v52, v65
	v_add_f32_e32 v65, v53, v65
	v_cvt_pk_bf16_f32 v134, v48, v49
	v_cvt_pk_bf16_f32 v135, v50, v51
	s_waitcnt lgkmcnt(13)
	v_mfma_f32_32x32x16_bf16 v[98:113], v[126:129], v[150:153], v[98:113]
	ds_read_b64_tr_b16 v[48:49], v189 offset:38912
	ds_read_b64_tr_b16 v[50:51], v189 offset:39424
	v_add_f32_e32 v65, v54, v65
	v_add_f32_e32 v65, v55, v65
	v_add_f32_e32 v65, v56, v65
	v_add_f32_e32 v65, v57, v65
	v_cvt_pk_bf16_f32 v136, v52, v53
	v_cvt_pk_bf16_f32 v137, v54, v55
	s_waitcnt lgkmcnt(14)
	v_mfma_f32_32x32x16_bf16 v[82:97], v[122:125], v[150:153], v[82:97]
	ds_read_b64_tr_b16 v[52:53], v189 offset:35840
	ds_read_b64_tr_b16 v[54:55], v189 offset:36352
	v_add_f32_e32 v65, v58, v65
	v_add_f32_e32 v65, v59, v65
	v_add_f32_e32 v65, v60, v65
	v_add_f32_e32 v65, v61, v65
	v_cvt_pk_bf16_f32 v130, v56, v57
	v_cvt_pk_bf16_f32 v131, v58, v59
	s_waitcnt lgkmcnt(14)
	v_mfma_f32_32x32x16_bf16 v[98:113], v[118:121], v[146:149], v[98:113]
	ds_read_b64_tr_b16 v[56:57], v189 offset:39936
	ds_read_b64_tr_b16 v[58:59], v189 offset:40448
	v_add_f32_e32 v65, v62, v65
	v_add_f32_e32 v65, v63, v65
	v_add_f32_e32 v65, 0, v65
	v_cvt_pk_bf16_f32 v132, v60, v61
	v_cvt_pk_bf16_f32 v133, v62, v63
	v_mfma_f32_32x32x16_bf16 v[82:97], v[114:117], v[146:149], v[82:97]
	s_add_u32 s20, s10, 0xba0000
	s_addc_u32 s21, s11, 0
	s_cmp_lg_u32 0, -1
	s_cselect_b32 s17, 0, 0
	s_add_i32 s17, s17, s19
	s_add_i32 s19, s17, 0x4000
	s_mov_b32 s22, m0
	s_mov_b32 m0, s19
	s_nop 0
	global_load_lds_dwordx4 v184, s[20:21]
	s_mov_b32 m0, s22
	s_add_u32 s20, s8, 0xb40000
	s_addc_u32 s21, s9, 0
	s_mov_b32 s19, m0
	s_mov_b32 m0, s15
	s_nop 0
	global_load_lds_dwordx4 v185, s[20:21]
	s_mov_b32 m0, s19
	v_add_f32_e32 v183, v64, v65
	s_waitcnt lgkmcnt(14)
	v_mfma_f32_32x32x16_bf16 v[0:15], v[142:145], v[174:177], v[0:15]
	v_exp_f32_e32 v98, v98
	v_exp_f32_e32 v99, v99
	v_exp_f32_e32 v100, v100
	v_exp_f32_e32 v101, v101
	s_waitcnt lgkmcnt(12)
	v_mfma_f32_32x32x16_bf16 v[16:31], v[142:145], v[178:181], v[16:31]
	v_exp_f32_e32 v102, v102
	v_exp_f32_e32 v103, v103
	v_exp_f32_e32 v104, v104
	v_exp_f32_e32 v105, v105
	ds_read_b128 v[60:63], v187
	ds_read_b128 v[78:81], v187 offset:512
	s_waitcnt lgkmcnt(12)
	v_mfma_f32_32x32x16_bf16 v[0:15], v[138:141], v[66:69], v[0:15]
	v_exp_f32_e32 v106, v106
	v_exp_f32_e32 v107, v107
	v_exp_f32_e32 v108, v108
	v_exp_f32_e32 v109, v109
	ds_read_b128 v[162:165], v187 offset:2048
	ds_read_b128 v[166:169], v187 offset:2560
	s_waitcnt lgkmcnt(12)
	v_mfma_f32_32x32x16_bf16 v[16:31], v[138:141], v[70:73], v[16:31]
	v_exp_f32_e32 v110, v110
	v_exp_f32_e32 v111, v111
	v_exp_f32_e32 v112, v112
	v_exp_f32_e32 v113, v113
	ds_read_b128 v[68:71], v187 offset:4096
	ds_read_b128 v[170:173], v187 offset:4608
	s_waitcnt lgkmcnt(12)
	v_mfma_f32_32x32x16_bf16 v[0:15], v[134:137], v[74:77], v[0:15]
	v_exp_f32_e32 v82, v82
	v_exp_f32_e32 v83, v83
	v_exp_f32_e32 v84, v84
	v_exp_f32_e32 v85, v85
	ds_read_b128 v[72:75], v187 offset:6144
	ds_read_b128 v[64:67], v187 offset:6656
	s_waitcnt lgkmcnt(12)
	v_mfma_f32_32x32x16_bf16 v[16:31], v[134:137], v[48:51], v[16:31]
	v_exp_f32_e32 v86, v86
	v_exp_f32_e32 v87, v87
	v_exp_f32_e32 v88, v88
	v_exp_f32_e32 v89, v89
	s_waitcnt lgkmcnt(10)
	v_mfma_f32_32x32x16_bf16 v[0:15], v[130:133], v[52:55], v[0:15]
	v_exp_f32_e32 v90, v90
	v_exp_f32_e32 v91, v91
	v_exp_f32_e32 v92, v92
	v_exp_f32_e32 v93, v93
	s_waitcnt lgkmcnt(8)
	v_mfma_f32_32x32x16_bf16 v[16:31], v[130:133], v[56:59], v[16:31]
	v_exp_f32_e32 v94, v94
	v_exp_f32_e32 v95, v95
	v_exp_f32_e32 v96, v96
	v_exp_f32_e32 v97, v97
	s_waitcnt vmcnt(2) lgkmcnt(0)
	s_barrier
	ds_read_b64_tr_b16 v[174:175], v189 offset:40960
	ds_read_b64_tr_b16 v[176:177], v189 offset:41472
	v_add_f32_e32 v48, v98, v99
	v_add_f32_e32 v48, v100, v48
	v_add_f32_e32 v48, v101, v48
	v_add_f32_e32 v48, v102, v48
	v_add_f32_e32 v48, v103, v48
	v_cvt_pk_bf16_f32 v142, v98, v99
	v_cvt_pk_bf16_f32 v143, v100, v101
	s_waitcnt lgkmcnt(9)
	v_mfma_f32_32x32x16_bf16 v[114:129], v[60:63], v[158:161], v[32:47]
	ds_read_b64_tr_b16 v[98:99], v189 offset:45056
	ds_read_b64_tr_b16 v[100:101], v189 offset:45568
	v_add_f32_e32 v48, v104, v48
	v_add_f32_e32 v48, v105, v48
	v_add_f32_e32 v48, v106, v48
	v_add_f32_e32 v130, v107, v48
	s_waitcnt lgkmcnt(10)
	v_mfma_f32_32x32x16_bf16 v[48:63], v[78:81], v[158:161], v[32:47]
	v_cvt_pk_bf16_f32 v144, v102, v103
	v_cvt_pk_bf16_f32 v145, v104, v105
	ds_read_b64_tr_b16 v[76:77], v189 offset:41984
	ds_read_b64_tr_b16 v[78:79], v189 offset:42496
	v_add_f32_e32 v80, v108, v130
	v_add_f32_e32 v80, v109, v80
	v_add_f32_e32 v80, v110, v80
	v_add_f32_e32 v80, v111, v80
	v_cvt_pk_bf16_f32 v138, v106, v107
	v_cvt_pk_bf16_f32 v139, v108, v109
	s_waitcnt lgkmcnt(11)
	v_mfma_f32_32x32x16_bf16 v[114:129], v[162:165], v[154:157], v[114:129]
	ds_read_b64_tr_b16 v[102:103], v189 offset:46080
	ds_read_b64_tr_b16 v[104:105], v189 offset:46592
	s_waitcnt lgkmcnt(12)
	v_mfma_f32_32x32x16_bf16 v[48:63], v[166:169], v[154:157], v[48:63]
	v_add_f32_e32 v80, v112, v80
	v_add_f32_e32 v80, v113, v80
	v_add_f32_e32 v80, v82, v80
	v_add_f32_e32 v80, v83, v80
	v_cvt_pk_bf16_f32 v140, v110, v111
	v_cvt_pk_bf16_f32 v141, v112, v113
	ds_read_b64_tr_b16 v[106:107], v189 offset:43008
	ds_read_b64_tr_b16 v[108:109], v189 offset:43520
	s_waitcnt lgkmcnt(13)
	v_mfma_f32_32x32x16_bf16 v[114:129], v[68:71], v[150:153], v[114:129]
	v_add_f32_e32 v68, v84, v80
	v_add_f32_e32 v68, v85, v68
	v_add_f32_e32 v68, v86, v68
	v_add_f32_e32 v80, v87, v68
	v_cvt_pk_bf16_f32 v134, v82, v83
	v_cvt_pk_bf16_f32 v135, v84, v85
	ds_read_b64_tr_b16 v[68:69], v189 offset:47104
	ds_read_b64_tr_b16 v[70:71], v189 offset:47616
	s_waitcnt lgkmcnt(14)
	v_mfma_f32_32x32x16_bf16 v[48:63], v[170:173], v[150:153], v[48:63]
	v_add_f32_e32 v80, v88, v80
	v_add_f32_e32 v80, v89, v80
	v_add_f32_e32 v80, v90, v80
	v_add_f32_e32 v80, v91, v80
	v_cvt_pk_bf16_f32 v136, v86, v87
	v_cvt_pk_bf16_f32 v137, v88, v89
	ds_read_b64_tr_b16 v[84:85], v189 offset:44032
	ds_read_b64_tr_b16 v[86:87], v189 offset:44544
	s_waitcnt lgkmcnt(14)
	v_mfma_f32_32x32x16_bf16 v[114:129], v[72:75], v[146:149], v[114:129]
	v_add_f32_e32 v72, v92, v80
	v_add_f32_e32 v72, v93, v72
	v_add_f32_e32 v72, v94, v72
	v_add_f32_e32 v80, v95, v72
	v_cvt_pk_bf16_f32 v130, v90, v91
	v_cvt_pk_bf16_f32 v131, v92, v93
	ds_read_b64_tr_b16 v[72:73], v189 offset:48128
	ds_read_b64_tr_b16 v[74:75], v189 offset:48640
	v_mfma_f32_32x32x16_bf16 v[48:63], v[64:67], v[146:149], v[48:63]
	v_add_f32_e32 v64, v96, v80
	v_add_f32_e32 v64, v97, v64
	v_add_f32_e32 v64, 0, v64
	v_cvt_pk_bf16_f32 v132, v94, v95
	v_cvt_pk_bf16_f32 v133, v96, v97
	s_add_u32 s10, s10, 0xbd0000
	s_addc_u32 s11, s11, 0
	s_mov_b32 s19, m0
	s_mov_b32 m0, s18
	s_nop 0
	global_load_lds_dwordx4 v184, s[10:11]
	s_mov_b32 m0, s19
	s_add_u32 s10, s8, 0xb70000
	s_addc_u32 s11, s9, 0
	s_add_i32 s18, s17, 0x8000
	s_mov_b32 s19, m0
	s_mov_b32 m0, s18
	s_nop 0
	global_load_lds_dwordx4 v185, s[10:11]
	s_mov_b32 m0, s19
	v_add_f32_e32 v178, v183, v64
	s_waitcnt lgkmcnt(14)
	v_mfma_f32_32x32x16_bf16 v[0:15], v[142:145], v[174:177], v[0:15]
	v_exp_f32_e32 v114, v114
	v_exp_f32_e32 v115, v115
	v_exp_f32_e32 v116, v116
	v_exp_f32_e32 v117, v117
	s_waitcnt lgkmcnt(12)
	v_mfma_f32_32x32x16_bf16 v[16:31], v[142:145], v[98:101], v[16:31]
	v_exp_f32_e32 v118, v118
	v_exp_f32_e32 v119, v119
	v_exp_f32_e32 v120, v120
	v_exp_f32_e32 v121, v121
	ds_read_b128 v[64:67], v187 offset:8192
	ds_read_b128 v[88:91], v187 offset:8704
	s_waitcnt lgkmcnt(12)
	v_mfma_f32_32x32x16_bf16 v[0:15], v[138:141], v[76:79], v[0:15]
	v_exp_f32_e32 v122, v122
	v_exp_f32_e32 v123, v123
	v_exp_f32_e32 v124, v124
	v_exp_f32_e32 v125, v125
	ds_read_b128 v[92:95], v187 offset:10240
	ds_read_b128 v[162:165], v187 offset:10752
	s_waitcnt lgkmcnt(12)
	v_mfma_f32_32x32x16_bf16 v[16:31], v[138:141], v[102:105], v[16:31]
	v_exp_f32_e32 v126, v126
	v_exp_f32_e32 v127, v127
	v_exp_f32_e32 v128, v128
	v_exp_f32_e32 v129, v129
	ds_read_b128 v[166:169], v187 offset:12288
	ds_read_b128 v[170:173], v187 offset:12800
	s_waitcnt lgkmcnt(12)
	v_mfma_f32_32x32x16_bf16 v[0:15], v[134:137], v[106:109], v[0:15]
	v_exp_f32_e32 v48, v48
	v_exp_f32_e32 v49, v49
	v_exp_f32_e32 v50, v50
	v_exp_f32_e32 v51, v51
	ds_read_b128 v[174:177], v187 offset:14336
	ds_read_b128 v[80:83], v187 offset:14848
	s_waitcnt lgkmcnt(12)
	v_mfma_f32_32x32x16_bf16 v[16:31], v[134:137], v[68:71], v[16:31]
	v_exp_f32_e32 v52, v52
	v_exp_f32_e32 v53, v53
	v_exp_f32_e32 v54, v54
	v_exp_f32_e32 v55, v55
	s_waitcnt lgkmcnt(10)
	v_mfma_f32_32x32x16_bf16 v[0:15], v[130:133], v[84:87], v[0:15]
	v_exp_f32_e32 v56, v56
	v_exp_f32_e32 v57, v57
	v_exp_f32_e32 v58, v58
	v_exp_f32_e32 v59, v59
	s_waitcnt lgkmcnt(8)
	v_mfma_f32_32x32x16_bf16 v[16:31], v[130:133], v[72:75], v[16:31]
	v_exp_f32_e32 v60, v60
	v_exp_f32_e32 v61, v61
	v_exp_f32_e32 v62, v62
	v_exp_f32_e32 v63, v63
	s_waitcnt vmcnt(2) lgkmcnt(0)
	s_barrier
	ds_read_b64_tr_b16 v[84:85], v189 offset:24576
	ds_read_b64_tr_b16 v[86:87], v189 offset:25088
	v_add_f32_e32 v68, v114, v115
	v_add_f32_e32 v68, v116, v68
	v_add_f32_e32 v68, v117, v68
	v_add_f32_e32 v68, v118, v68
	v_add_f32_e32 v68, v119, v68
	v_cvt_pk_bf16_f32 v142, v114, v115
	v_cvt_pk_bf16_f32 v143, v116, v117
	s_waitcnt lgkmcnt(9)
	v_mfma_f32_32x32x16_bf16 v[96:111], v[64:67], v[158:161], v[32:47]
	ds_read_b64_tr_b16 v[112:113], v189 offset:28672
	ds_read_b64_tr_b16 v[114:115], v189 offset:29184
	v_add_f32_e32 v64, v120, v68
	v_add_f32_e32 v64, v121, v64
	v_add_f32_e32 v64, v122, v64
	v_add_f32_e32 v116, v123, v64
	v_cvt_pk_bf16_f32 v144, v118, v119
	v_cvt_pk_bf16_f32 v145, v120, v121
	s_waitcnt lgkmcnt(10)
	v_mfma_f32_32x32x16_bf16 v[64:79], v[88:91], v[158:161], v[32:47]
	ds_read_b64_tr_b16 v[88:89], v189 offset:25600
	ds_read_b64_tr_b16 v[90:91], v189 offset:26112
	s_waitcnt lgkmcnt(11)
	v_mfma_f32_32x32x16_bf16 v[96:111], v[92:95], v[154:157], v[96:111]
	v_add_f32_e32 v92, v124, v116
	v_add_f32_e32 v92, v125, v92
	v_add_f32_e32 v92, v126, v92
	v_add_f32_e32 v116, v127, v92
	v_cvt_pk_bf16_f32 v138, v122, v123
	v_cvt_pk_bf16_f32 v139, v124, v125
	ds_read_b64_tr_b16 v[92:93], v189 offset:29696
	ds_read_b64_tr_b16 v[94:95], v189 offset:30208
	v_add_f32_e32 v116, v128, v116
	v_add_f32_e32 v116, v129, v116
	v_add_f32_e32 v116, v48, v116
	v_add_f32_e32 v120, v49, v116
	v_cvt_pk_bf16_f32 v140, v126, v127
	v_cvt_pk_bf16_f32 v141, v128, v129
	s_waitcnt lgkmcnt(12)
	v_mfma_f32_32x32x16_bf16 v[64:79], v[162:165], v[154:157], v[64:79]
	ds_read_b64_tr_b16 v[116:117], v189 offset:26624
	ds_read_b64_tr_b16 v[118:119], v189 offset:27136
	v_add_f32_e32 v120, v50, v120
	v_add_f32_e32 v120, v51, v120
	v_add_f32_e32 v120, v52, v120
	v_add_f32_e32 v120, v53, v120
	v_cvt_pk_bf16_f32 v134, v48, v49
	v_cvt_pk_bf16_f32 v135, v50, v51
	s_waitcnt lgkmcnt(13)
	v_mfma_f32_32x32x16_bf16 v[96:111], v[166:169], v[150:153], v[96:111]
	ds_read_b64_tr_b16 v[48:49], v189 offset:30720
	ds_read_b64_tr_b16 v[50:51], v189 offset:31232
	v_add_f32_e32 v120, v54, v120
	v_add_f32_e32 v120, v55, v120
	v_add_f32_e32 v120, v56, v120
	v_add_f32_e32 v120, v57, v120
	v_cvt_pk_bf16_f32 v136, v52, v53
	v_cvt_pk_bf16_f32 v137, v54, v55
	s_waitcnt lgkmcnt(14)
	v_mfma_f32_32x32x16_bf16 v[64:79], v[170:173], v[150:153], v[64:79]
	ds_read_b64_tr_b16 v[52:53], v189 offset:27648
	ds_read_b64_tr_b16 v[54:55], v189 offset:28160
	v_add_f32_e32 v120, v58, v120
	v_add_f32_e32 v120, v59, v120
	v_add_f32_e32 v120, v60, v120
	v_add_f32_e32 v120, v61, v120
	v_cvt_pk_bf16_f32 v130, v56, v57
	v_cvt_pk_bf16_f32 v131, v58, v59
	s_waitcnt lgkmcnt(14)
	v_mfma_f32_32x32x16_bf16 v[96:111], v[174:177], v[146:149], v[96:111]
	ds_read_b64_tr_b16 v[56:57], v189 offset:31744
	ds_read_b64_tr_b16 v[58:59], v189 offset:32256
	v_mfma_f32_32x32x16_bf16 v[64:79], v[80:83], v[146:149], v[64:79]
	v_add_f32_e32 v80, v62, v120
	v_add_f32_e32 v80, v63, v80
	v_add_f32_e32 v80, 0, v80
	v_cvt_pk_bf16_f32 v132, v60, v61
	v_cvt_pk_bf16_f32 v133, v62, v63
	s_add_u32 s10, s8, 0xba0000
	s_addc_u32 s11, s9, 0
	s_add_i32 s17, s17, 0xa000
	s_mov_b32 s18, m0
	s_mov_b32 m0, s17
	s_nop 0
	global_load_lds_dwordx4 v185, s[10:11]
	s_mov_b32 m0, s18
	v_add_f32_e32 v128, v178, v80
	s_waitcnt lgkmcnt(14)
	v_mfma_f32_32x32x16_bf16 v[0:15], v[142:145], v[84:87], v[0:15]
	v_exp_f32_e32 v96, v96
	v_exp_f32_e32 v97, v97
	v_exp_f32_e32 v98, v98
	v_exp_f32_e32 v99, v99
	s_waitcnt lgkmcnt(12)
	v_mfma_f32_32x32x16_bf16 v[16:31], v[142:145], v[112:115], v[16:31]
	v_exp_f32_e32 v100, v100
	v_exp_f32_e32 v101, v101
	v_exp_f32_e32 v102, v102
	v_exp_f32_e32 v103, v103
	ds_read_b128 v[60:63], v187 offset:16384
	ds_read_b128 v[120:123], v187 offset:16896
	s_waitcnt lgkmcnt(12)
	v_mfma_f32_32x32x16_bf16 v[0:15], v[138:141], v[88:91], v[0:15]
	v_exp_f32_e32 v104, v104
	v_exp_f32_e32 v105, v105
	v_exp_f32_e32 v106, v106
	v_exp_f32_e32 v107, v107
	ds_read_b128 v[124:127], v187 offset:18432
	ds_read_b128 v[162:165], v187 offset:18944
	s_waitcnt lgkmcnt(12)
	v_mfma_f32_32x32x16_bf16 v[16:31], v[138:141], v[92:95], v[16:31]
	v_exp_f32_e32 v108, v108
	v_exp_f32_e32 v109, v109
	v_exp_f32_e32 v110, v110
	v_exp_f32_e32 v111, v111
	ds_read_b128 v[166:169], v187 offset:20480
	ds_read_b128 v[170:173], v187 offset:20992
	s_waitcnt lgkmcnt(12)
	v_mfma_f32_32x32x16_bf16 v[0:15], v[134:137], v[116:119], v[0:15]
	v_exp_f32_e32 v64, v64
	v_exp_f32_e32 v65, v65
	v_exp_f32_e32 v66, v66
	v_exp_f32_e32 v67, v67
	ds_read_b128 v[116:119], v187 offset:22528
	ds_read_b128 v[112:115], v187 offset:23040
	s_waitcnt lgkmcnt(12)
	v_mfma_f32_32x32x16_bf16 v[16:31], v[134:137], v[48:51], v[16:31]
	v_exp_f32_e32 v68, v68
	v_exp_f32_e32 v69, v69
	v_exp_f32_e32 v70, v70
	v_exp_f32_e32 v71, v71
	s_waitcnt lgkmcnt(10)
	v_mfma_f32_32x32x16_bf16 v[0:15], v[130:133], v[52:55], v[0:15]
	v_exp_f32_e32 v72, v72
	v_exp_f32_e32 v73, v73
	v_exp_f32_e32 v74, v74
	v_exp_f32_e32 v75, v75
	s_waitcnt lgkmcnt(8)
	v_mfma_f32_32x32x16_bf16 v[16:31], v[130:133], v[56:59], v[16:31]
	v_exp_f32_e32 v76, v76
	v_exp_f32_e32 v77, v77
	v_exp_f32_e32 v78, v78
	v_exp_f32_e32 v79, v79
	s_waitcnt vmcnt(1) lgkmcnt(0)
	s_barrier
	ds_read_b64_tr_b16 v[174:175], v189 offset:32768
	ds_read_b64_tr_b16 v[176:177], v189 offset:33280
	v_add_f32_e32 v48, v96, v97
	v_add_f32_e32 v48, v98, v48
	v_add_f32_e32 v48, v99, v48
	v_add_f32_e32 v48, v100, v48
	v_add_f32_e32 v48, v101, v48
	v_cvt_pk_bf16_f32 v142, v96, v97
	v_cvt_pk_bf16_f32 v143, v98, v99
	s_waitcnt lgkmcnt(9)
	v_mfma_f32_32x32x16_bf16 v[80:95], v[60:63], v[158:161], v[32:47]
	ds_read_b64_tr_b16 v[96:97], v189 offset:36864
	ds_read_b64_tr_b16 v[98:99], v189 offset:37376
	v_add_f32_e32 v48, v102, v48
	v_add_f32_e32 v48, v103, v48
	v_add_f32_e32 v48, v104, v48
	v_add_f32_e32 v129, v105, v48
	s_waitcnt lgkmcnt(10)
	v_mfma_f32_32x32x16_bf16 v[48:63], v[120:123], v[158:161], v[32:47]
	v_cvt_pk_bf16_f32 v144, v100, v101
	v_cvt_pk_bf16_f32 v145, v102, v103
	ds_read_b64_tr_b16 v[100:101], v189 offset:33792
	ds_read_b64_tr_b16 v[102:103], v189 offset:34304
	v_add_f32_e32 v120, v106, v129
	v_add_f32_e32 v120, v107, v120
	v_add_f32_e32 v120, v108, v120
	v_add_f32_e32 v120, v109, v120
	v_cvt_pk_bf16_f32 v138, v104, v105
	v_cvt_pk_bf16_f32 v139, v106, v107
	s_waitcnt lgkmcnt(11)
	v_mfma_f32_32x32x16_bf16 v[80:95], v[124:127], v[154:157], v[80:95]
	ds_read_b64_tr_b16 v[104:105], v189 offset:37888
	ds_read_b64_tr_b16 v[106:107], v189 offset:38400
	s_waitcnt lgkmcnt(12)
	v_mfma_f32_32x32x16_bf16 v[48:63], v[162:165], v[154:157], v[48:63]
	v_add_f32_e32 v120, v110, v120
	v_add_f32_e32 v120, v111, v120
	v_add_f32_e32 v120, v64, v120
	v_add_f32_e32 v124, v65, v120
	v_cvt_pk_bf16_f32 v140, v108, v109
	v_cvt_pk_bf16_f32 v141, v110, v111
	ds_read_b64_tr_b16 v[120:121], v189 offset:34816
	ds_read_b64_tr_b16 v[122:123], v189 offset:35328
	v_add_f32_e32 v108, v66, v124
	v_add_f32_e32 v108, v67, v108
	v_add_f32_e32 v108, v68, v108
	v_add_f32_e32 v108, v69, v108
	v_cvt_pk_bf16_f32 v134, v64, v65
	v_cvt_pk_bf16_f32 v135, v66, v67
	s_waitcnt lgkmcnt(13)
	v_mfma_f32_32x32x16_bf16 v[80:95], v[166:169], v[150:153], v[80:95]
	ds_read_b64_tr_b16 v[64:65], v189 offset:38912
	ds_read_b64_tr_b16 v[66:67], v189 offset:39424
	s_waitcnt lgkmcnt(14)
	v_mfma_f32_32x32x16_bf16 v[48:63], v[170:173], v[150:153], v[48:63]
	v_add_f32_e32 v108, v70, v108
	v_add_f32_e32 v108, v71, v108
	v_add_f32_e32 v108, v72, v108
	v_add_f32_e32 v108, v73, v108
	v_cvt_pk_bf16_f32 v136, v68, v69
	v_cvt_pk_bf16_f32 v137, v70, v71
	ds_read_b64_tr_b16 v[68:69], v189 offset:35840
	ds_read_b64_tr_b16 v[70:71], v189 offset:36352
	v_add_f32_e32 v108, v74, v108
	v_add_f32_e32 v108, v75, v108
	v_add_f32_e32 v108, v76, v108
	v_add_f32_e32 v108, v77, v108
	v_cvt_pk_bf16_f32 v130, v72, v73
	v_cvt_pk_bf16_f32 v131, v74, v75
	s_waitcnt lgkmcnt(14)
	v_mfma_f32_32x32x16_bf16 v[80:95], v[116:119], v[146:149], v[80:95]
	ds_read_b64_tr_b16 v[72:73], v189 offset:39936
	ds_read_b64_tr_b16 v[74:75], v189 offset:40448
	v_mfma_f32_32x32x16_bf16 v[48:63], v[112:115], v[146:149], v[48:63]
	v_add_f32_e32 v108, v78, v108
	v_add_f32_e32 v108, v79, v108
	v_add_f32_e32 v108, 0, v108
	v_cvt_pk_bf16_f32 v132, v76, v77
	v_cvt_pk_bf16_f32 v133, v78, v79
	s_add_u32 s8, s8, 0xbd0000
	s_addc_u32 s9, s9, 0
	s_mov_b32 s10, m0
	s_mov_b32 m0, s15
	s_nop 0
	global_load_lds_dwordx4 v185, s[8:9]
	s_mov_b32 m0, s10
	v_add_f32_e32 v108, v128, v108
	s_waitcnt lgkmcnt(14)
	v_mfma_f32_32x32x16_bf16 v[0:15], v[142:145], v[174:177], v[0:15]
	v_exp_f32_e32 v80, v80
	v_exp_f32_e32 v81, v81
	v_exp_f32_e32 v82, v82
	v_exp_f32_e32 v83, v83
	s_waitcnt lgkmcnt(12)
	v_mfma_f32_32x32x16_bf16 v[16:31], v[142:145], v[96:99], v[16:31]
	v_exp_f32_e32 v84, v84
	v_exp_f32_e32 v85, v85
	v_exp_f32_e32 v86, v86
	v_exp_f32_e32 v87, v87
	ds_read_b128 v[110:113], v187
	ds_read_b128 v[114:117], v187 offset:512
	s_waitcnt lgkmcnt(12)
	v_mfma_f32_32x32x16_bf16 v[0:15], v[138:141], v[100:103], v[0:15]
	v_exp_f32_e32 v88, v88
	v_exp_f32_e32 v89, v89
	v_exp_f32_e32 v90, v90
	v_exp_f32_e32 v91, v91
	ds_read_b128 v[124:127], v187 offset:2048
	ds_read_b128 v[162:165], v187 offset:2560
	s_waitcnt lgkmcnt(12)
	v_mfma_f32_32x32x16_bf16 v[16:31], v[138:141], v[104:107], v[16:31]
	v_exp_f32_e32 v92, v92
	v_exp_f32_e32 v93, v93
	v_exp_f32_e32 v94, v94
	v_exp_f32_e32 v95, v95
	ds_read_b128 v[166:169], v187 offset:4096
	ds_read_b128 v[170:173], v187 offset:4608
	s_waitcnt lgkmcnt(12)
	v_mfma_f32_32x32x16_bf16 v[0:15], v[134:137], v[120:123], v[0:15]
	v_exp_f32_e32 v48, v48
	v_exp_f32_e32 v49, v49
	v_exp_f32_e32 v50, v50
	v_exp_f32_e32 v51, v51
	ds_read_b128 v[118:121], v187 offset:6144
	ds_read_b128 v[104:107], v187 offset:6656
	s_waitcnt lgkmcnt(12)
	v_mfma_f32_32x32x16_bf16 v[16:31], v[134:137], v[64:67], v[16:31]
	v_exp_f32_e32 v52, v52
	v_exp_f32_e32 v53, v53
	v_exp_f32_e32 v54, v54
	v_exp_f32_e32 v55, v55
	s_waitcnt lgkmcnt(10)
	v_mfma_f32_32x32x16_bf16 v[0:15], v[130:133], v[68:71], v[0:15]
	v_exp_f32_e32 v56, v56
	v_exp_f32_e32 v57, v57
	v_exp_f32_e32 v58, v58
	v_exp_f32_e32 v59, v59
	s_waitcnt lgkmcnt(8)
	v_mfma_f32_32x32x16_bf16 v[16:31], v[130:133], v[72:75], v[16:31]
	v_exp_f32_e32 v60, v60
	v_exp_f32_e32 v61, v61
	v_exp_f32_e32 v62, v62
	v_exp_f32_e32 v63, v63
	s_waitcnt vmcnt(0) lgkmcnt(0)
	s_barrier
;     ...
;   { float sacc = pB0[0] + pB0[1]; _Pragma("unroll") for (int r = 2; r < 16; ++r) sacc += pB0[r]; _Pragma("unroll") for (int r = 0; r < 16; ++r) sacc += pB1[r]; l_reg += sacc;
	ds_read_b64_tr_b16 v[96:97], v189 offset:40960
	ds_read_b64_tr_b16 v[98:99], v189 offset:41472
	v_add_f32_e32 v64, v80, v81
	v_add_f32_e32 v64, v82, v64
	v_add_f32_e32 v64, v83, v64
	v_add_f32_e32 v64, v84, v64
	v_add_f32_e32 v100, v85, v64
	v_cvt_pk_bf16_f32 v142, v80, v81
	v_cvt_pk_bf16_f32 v143, v82, v83
	s_waitcnt lgkmcnt(9)
	v_mfma_f32_32x32x16_bf16 v[64:79], v[110:113], v[158:161], v[32:47]
	ds_read_b64_tr_b16 v[80:81], v189 offset:45056
	ds_read_b64_tr_b16 v[82:83], v189 offset:45568
	s_waitcnt lgkmcnt(10)
	v_mfma_f32_32x32x16_bf16 v[32:47], v[114:117], v[158:161], v[32:47]
	v_add_f32_e32 v100, v86, v100
	v_add_f32_e32 v100, v87, v100
	v_add_f32_e32 v100, v88, v100
	v_add_f32_e32 v109, v89, v100
	v_cvt_pk_bf16_f32 v144, v84, v85
	v_cvt_pk_bf16_f32 v145, v86, v87
	ds_read_b64_tr_b16 v[100:101], v189 offset:41984
	ds_read_b64_tr_b16 v[102:103], v189 offset:42496
	v_add_f32_e32 v84, v90, v109
	v_add_f32_e32 v84, v91, v84
	v_add_f32_e32 v84, v92, v84
	v_add_f32_e32 v109, v93, v84
	v_cvt_pk_bf16_f32 v138, v88, v89
	v_cvt_pk_bf16_f32 v139, v90, v91
	s_waitcnt lgkmcnt(11)
	v_mfma_f32_32x32x16_bf16 v[64:79], v[124:127], v[154:157], v[64:79]
	ds_read_b64_tr_b16 v[84:85], v189 offset:46080
	ds_read_b64_tr_b16 v[86:87], v189 offset:46592
	s_waitcnt lgkmcnt(12)
	v_mfma_f32_32x32x16_bf16 v[32:47], v[162:165], v[154:157], v[32:47]
	v_add_f32_e32 v88, v94, v109
	v_add_f32_e32 v88, v95, v88
	v_add_f32_e32 v88, v48, v88
	v_add_f32_e32 v109, v49, v88
	v_cvt_pk_bf16_f32 v140, v92, v93
	v_cvt_pk_bf16_f32 v141, v94, v95
	ds_read_b64_tr_b16 v[88:89], v189 offset:43008
	ds_read_b64_tr_b16 v[90:91], v189 offset:43520
	v_add_f32_e32 v92, v50, v109
	v_add_f32_e32 v92, v51, v92
	v_add_f32_e32 v92, v52, v92
	v_add_f32_e32 v92, v53, v92
	v_cvt_pk_bf16_f32 v134, v48, v49
	v_cvt_pk_bf16_f32 v135, v50, v51
	s_waitcnt lgkmcnt(13)
	v_mfma_f32_32x32x16_bf16 v[64:79], v[166:169], v[150:153], v[64:79]
	ds_read_b64_tr_b16 v[48:49], v189 offset:47104
	ds_read_b64_tr_b16 v[50:51], v189 offset:47616
	s_waitcnt lgkmcnt(14)
	v_mfma_f32_32x32x16_bf16 v[32:47], v[170:173], v[150:153], v[32:47]
	v_add_f32_e32 v92, v54, v92
	v_add_f32_e32 v92, v55, v92
	v_add_f32_e32 v92, v56, v92
	v_add_f32_e32 v109, v57, v92
	v_cvt_pk_bf16_f32 v136, v52, v53
	v_cvt_pk_bf16_f32 v137, v54, v55
	ds_read_b64_tr_b16 v[92:93], v189 offset:44032
	ds_read_b64_tr_b16 v[94:95], v189 offset:44544
	v_add_f32_e32 v52, v58, v109
	v_add_f32_e32 v52, v59, v52
	v_add_f32_e32 v52, v60, v52
	v_add_f32_e32 v109, v61, v52
	v_cvt_pk_bf16_f32 v130, v56, v57
	v_cvt_pk_bf16_f32 v131, v58, v59
	s_waitcnt lgkmcnt(14)
	v_mfma_f32_32x32x16_bf16 v[64:79], v[118:121], v[146:149], v[64:79]
	ds_read_b64_tr_b16 v[52:53], v189 offset:48128
	ds_read_b64_tr_b16 v[54:55], v189 offset:48640
	v_mfma_f32_32x32x16_bf16 v[32:47], v[104:107], v[146:149], v[32:47]
	v_add_f32_e32 v56, v62, v109
	v_add_f32_e32 v56, v63, v56
	v_add_f32_e32 v56, 0, v56
	v_cvt_pk_bf16_f32 v132, v60, v61
	v_cvt_pk_bf16_f32 v133, v62, v63
	s_nop 3
	v_exp_f32_e32 v64, v64
	v_exp_f32_e32 v65, v65
	v_exp_f32_e32 v66, v66
	v_exp_f32_e32 v67, v67
	s_nop 0
	v_exp_f32_e32 v68, v68
	v_exp_f32_e32 v69, v69
	v_exp_f32_e32 v70, v70
	v_exp_f32_e32 v71, v71
	s_nop 0
	v_exp_f32_e32 v72, v72
	v_exp_f32_e32 v73, v73
	v_exp_f32_e32 v74, v74
	v_exp_f32_e32 v75, v75
	s_nop 0
	v_exp_f32_e32 v76, v76
	v_exp_f32_e32 v77, v77
	v_exp_f32_e32 v78, v78
	v_exp_f32_e32 v79, v79
	v_exp_f32_e32 v32, v32
	v_exp_f32_e32 v33, v33
	v_exp_f32_e32 v34, v34
	v_exp_f32_e32 v35, v35
	s_nop 0
	v_exp_f32_e32 v36, v36
	v_exp_f32_e32 v37, v37
	v_exp_f32_e32 v38, v38
	v_exp_f32_e32 v39, v39
	s_nop 0
	v_exp_f32_e32 v40, v40
	v_exp_f32_e32 v41, v41
	v_exp_f32_e32 v42, v42
	v_exp_f32_e32 v43, v43
	s_nop 0
	v_exp_f32_e32 v44, v44
	v_exp_f32_e32 v45, v45
	v_exp_f32_e32 v46, v46
	v_exp_f32_e32 v47, v47
	s_waitcnt lgkmcnt(14)
; #define SBAR() __builtin_amdgcn_sched_barrier(0)
;   #define RESC() do { if constexpr (!NOMAX) if (resc) { asm volatile("s_waitcnt lgkmcnt(0)" ::: "memory"); \
;       _Pragma("unroll") for (int d_ = 0; d_ < 2 * DV2; ++d_) _Pragma("unroll") for (int r = 0; r < 16; ++r) o[d_][r] *= wsf[crow(r, hi)]; } } while (0)
;   #define PKW(P, B) cvtpk_s(P[B], P[B + 1])
; __device__ __forceinline__ void pv(f32x16* o, int vb, bf16x8 pa0, bf16x8 pa1, bf16x8 pa2, bf16x8 pa3) {
;   #pragma unroll
;   for (int d0 = 0; d0 < 2; ++d0) { s16x4 lo[4], hi[4];
;     #pragma unroll
;     for (int ks = 0; ks < 4; ++ks) {
;       asm volatile("ds_read_b64_tr_b16 %0,%1 offset:%c2" : "=&v"(lo[ks]) : "v"(vb), "i"(d0 * 4096 + ks * 1024) : "memory");
;       asm volatile("ds_read_b64_tr_b16 %0,%1 offset:%c2" : "=&v"(hi[ks]) : "v"(vb), "i"(d0 * 4096 + ks * 1024 + 512) : "memory"); }
;     asm volatile("s_waitcnt lgkmcnt(0)" ::: "memory"); SBAR();
;     ...
;     o[d0] = __builtin_amdgcn_mfma_f32_32x32x16_bf16(pa0, PK(0), o[d0], 0, 0, 0);
;     o[d0] = __builtin_amdgcn_mfma_f32_32x32x16_bf16(pa1, PK(1), o[d0], 0, 0, 0);
;     o[d0] = __builtin_amdgcn_mfma_f32_32x32x16_bf16(pa2, PK(2), o[d0], 0, 0, 0);
;     o[d0] = __builtin_amdgcn_mfma_f32_32x32x16_bf16(pa3, PK(3), o[d0], 0, 0, 0);
;     ...
;   }
; }
;     ...
;   }
;   STEP(pB0, pB1, pA0, pA1, NT - 1, false, false, false); RESC();
;   { float sacc = pB0[0] + pB0[1]; _Pragma("unroll") for (int r = 2; r < 16; ++r) sacc += pB0[r]; _Pragma("unroll") for (int r = 0; r < 16; ++r) sacc += pB1[r]; l_reg += sacc;
;     pw0 = (u32x4){PKW(pB0, 0), PKW(pB0, 2), PKW(pB0, 4), PKW(pB0, 6)}; pw1 = (u32x4){PKW(pB0, 8), PKW(pB0, 10), PKW(pB0, 12), PKW(pB0, 14)}; pw2 = (u32x4){PKW(pB1, 0), PKW(pB1, 2), PKW(pB1, 4), PKW(pB1, 6)}; pw3 = (u32x4){PKW(pB1, 8), PKW(pB1, 10), PKW(pB1, 12), PKW(pB1, 14)};
;     SBAR(); pv(o, vb0 + DV2 * sl_cur, PAF(0), PAF(1), PAF(2), PAF(3)); if constexpr (DV2 == 2) pv(o + 2, vb0 + DV2 * sl_cur + 8192, PAF(0), PAF(1), PAF(2), PAF(3)); }
;     ...
;   { auto rr = __builtin_amdgcn_permlane32_swap(__float_as_uint(l_reg), __float_as_uint(l_reg), false, false); l_reg = __uint_as_float(rr[0]) + __uint_as_float(rr[1]); }
;   int lane_e; asm volatile("v_mbcnt_lo_u32_b32 %0, -1, 0\n\tv_mbcnt_hi_u32_b32 %0, -1, %0" : "=v"(lane_e));
;   const int r32e = lane_e & 31, hie = lane_e >> 5;
;   if (hie == 0) wsf[32 + r32e] = l_reg; asm volatile("s_waitcnt lgkmcnt(0)" ::: "memory");
	v_mfma_f32_32x32x16_bf16 v[0:15], v[142:145], v[96:99], v[0:15]
	v_add_f32_e32 v57, v64, v65
	v_add_f32_e32 v57, v66, v57
	v_add_f32_e32 v57, v67, v57
	v_add_f32_e32 v57, v68, v57
	v_add_f32_e32 v57, v69, v57
	v_add_f32_e32 v57, v70, v57
	v_add_f32_e32 v57, v71, v57
	s_waitcnt lgkmcnt(12)
	v_mfma_f32_32x32x16_bf16 v[16:31], v[142:145], v[80:83], v[16:31]
	v_add_f32_e32 v57, v72, v57
	v_add_f32_e32 v57, v73, v57
	v_add_f32_e32 v57, v74, v57
	v_add_f32_e32 v57, v75, v57
	v_add_f32_e32 v57, v76, v57
	v_add_f32_e32 v57, v77, v57
	v_add_f32_e32 v57, v78, v57
	s_waitcnt lgkmcnt(10)
	v_mfma_f32_32x32x16_bf16 v[0:15], v[138:141], v[100:103], v[0:15]
	v_add_f32_e32 v57, v79, v57
	v_add_f32_e32 v57, v32, v57
	v_add_f32_e32 v57, v33, v57
	v_add_f32_e32 v57, v34, v57
	v_add_f32_e32 v57, v35, v57
	v_add_f32_e32 v57, v36, v57
	v_add_f32_e32 v57, v37, v57
	s_waitcnt lgkmcnt(8)
	v_mfma_f32_32x32x16_bf16 v[16:31], v[138:141], v[84:87], v[16:31]
	v_add_f32_e32 v57, v38, v57
	v_add_f32_e32 v57, v39, v57
	v_add_f32_e32 v57, v40, v57
	v_add_f32_e32 v57, v41, v57
	v_add_f32_e32 v57, v42, v57
	v_add_f32_e32 v57, v43, v57
	v_add_f32_e32 v57, v44, v57
	s_waitcnt lgkmcnt(6)
	v_mfma_f32_32x32x16_bf16 v[0:15], v[134:137], v[88:91], v[0:15]
	v_add_f32_e32 v57, v45, v57
	v_add_f32_e32 v57, v46, v57
	v_add_f32_e32 v57, v47, v57
	v_add_f32_e32 v56, v108, v56
	v_add_f32_e32 v56, v56, v57
	v_cvt_pk_bf16_f32 v32, v32, v33
	v_cvt_pk_bf16_f32 v33, v34, v35
	s_waitcnt lgkmcnt(4)
	v_mfma_f32_32x32x16_bf16 v[16:31], v[134:137], v[48:51], v[16:31]
	v_cvt_pk_bf16_f32 v58, v64, v65
	v_cvt_pk_bf16_f32 v59, v66, v67
	v_cvt_pk_bf16_f32 v60, v68, v69
	v_cvt_pk_bf16_f32 v61, v70, v71
	v_cvt_pk_bf16_f32 v62, v72, v73
	v_cvt_pk_bf16_f32 v63, v74, v75
	v_cvt_pk_bf16_f32 v64, v76, v77
	s_waitcnt lgkmcnt(2)
	v_mfma_f32_32x32x16_bf16 v[0:15], v[130:133], v[92:95], v[0:15]
	v_cvt_pk_bf16_f32 v65, v78, v79
	v_cvt_pk_bf16_f32 v34, v36, v37
	v_cvt_pk_bf16_f32 v35, v38, v39
	v_cvt_pk_bf16_f32 v36, v40, v41
	v_cvt_pk_bf16_f32 v37, v42, v43
	v_cvt_pk_bf16_f32 v38, v44, v45
	v_cvt_pk_bf16_f32 v39, v46, v47
	s_waitcnt lgkmcnt(0)
	v_mfma_f32_32x32x16_bf16 v[16:31], v[130:133], v[52:55], v[16:31]
	ds_read_b64_tr_b16 v[40:41],v188 offset:0
	ds_read_b64_tr_b16 v[42:43],v188 offset:512
	ds_read_b64_tr_b16 v[44:45],v188 offset:1024
	ds_read_b64_tr_b16 v[46:47],v188 offset:1536
	ds_read_b64_tr_b16 v[48:49],v188 offset:2048
	ds_read_b64_tr_b16 v[50:51],v188 offset:2560
	ds_read_b64_tr_b16 v[52:53],v188 offset:3072
	ds_read_b64_tr_b16 v[54:55],v188 offset:3584
	s_waitcnt lgkmcnt(0)
	s_nop 0
	v_mfma_f32_32x32x16_bf16 v[0:15], v[58:61], v[40:43], v[0:15]
	ds_read_b64_tr_b16 v[40:41],v188 offset:4096
	ds_read_b64_tr_b16 v[42:43],v188 offset:4608
	v_mfma_f32_32x32x16_bf16 v[0:15], v[62:65], v[44:47], v[0:15]
	ds_read_b64_tr_b16 v[44:45],v188 offset:5120
	ds_read_b64_tr_b16 v[46:47],v188 offset:5632
	v_mfma_f32_32x32x16_bf16 v[0:15], v[32:35], v[48:51], v[0:15]
	ds_read_b64_tr_b16 v[48:49],v188 offset:6144
	ds_read_b64_tr_b16 v[50:51],v188 offset:6656
	v_mfma_f32_32x32x16_bf16 v[0:15], v[36:39], v[52:55], v[0:15]
	ds_read_b64_tr_b16 v[52:53],v188 offset:7168
	ds_read_b64_tr_b16 v[54:55],v188 offset:7680
	s_waitcnt lgkmcnt(0)
	v_mfma_f32_32x32x16_bf16 v[16:31], v[58:61], v[40:43], v[16:31]
	v_mfma_f32_32x32x16_bf16 v[16:31], v[62:65], v[44:47], v[16:31]
	v_mfma_f32_32x32x16_bf16 v[16:31], v[32:35], v[48:51], v[16:31]
	v_mov_b32_e32 v33, v56
	s_nop 1
	v_permlane32_swap_b32_e32 v56, v33
	v_mbcnt_lo_u32_b32 v32, -1, 0
	v_mbcnt_hi_u32_b32 v32, -1, v32
	s_nop 0
	v_cmp_gt_u32_e32 vcc, 32, v32
	v_mfma_f32_32x32x16_bf16 v[16:31], v[36:39], v[52:55], v[16:31]
	s_and_saveexec_b64 s[8:9], vcc
	s_cbranch_execz .LBB0_968
	v_add_f32_e32 v33, v56, v33
	v_lshl_add_u32 v34, v32, 2, s16
	ds_write_b32 v34, v33 offset:49280
	s_branch .LBB0_968
